# converted K-loops use v_mfma_f32_16x16x32_bf16 (same bf16 operands, f32 accumulate) with own accumulator-to-LDS writes
# speedup vs baseline: 1.1052x; 1.0125x over previous
; DI int BID() { int b = (int)__builtin_amdgcn_workgroup_id_x(); asm volatile("" : "+s"(b)); return b; }
; DI void tile_ffn2(const Params& p, int l, const Chunk& ck, int tile, int next, PF& pf, char* smem) {
;     ...
;   { const u16* Ap; const u16* Wt; ffn2_ptrs(p, l, tile, Ap, Wt); gemm_run<64>(pf, Ap, 4096, Wt, acc, smem); }
;   if (next >= 0) { const u16* An; const u16* Wn; ffn2_ptrs(p, l, next, An, Wn); gemm_issue(pf, An, 4096, Wn, 4096); }
;   acc_to_cs(acc, Cs);
; DI void run_phase(const Params& p, int ph, int l, int c, char* smem) {
;     ...
;       PF pf; int t = BID();
;       if (t < MTN * 8) { const u16* A0; const u16* W0; ffn2_ptrs(p, l, t, A0, W0); gemm_issue(pf, A0, 4096, W0, 4096); }
;       for (; t < MTN * 8; t += gridDim.x) { const int tn = t + (int)gridDim.x; tile_ffn2(p, l, ck, t, tn < MTN * 8 ? tn : -1, pf, smem); }
.LBB1_205:
	s_cmp_lg_u32 s16, 0
	s_cbranch_scc1 .Lffn2_p2done
	s_mov_b32 s16, 1
	v_mov_b32_e32 v0, v172
	s_add_u32 s26, s26, 0x80
	s_and_b32 s36, s26, 0xffffff80
	s_mov_b32 s37, 0
	s_waitcnt lgkmcnt(0)
	s_barrier
	s_branch .Lffn2_epi2

; DI int TID() { int t = (int)__builtin_amdgcn_workitem_id_x(); asm volatile("" : "+v"(t)); return t; }
; DI void zero_acc(f32x16 (&acc)[2][2]) {
; #pragma unroll
;   for (int a = 0; a < 2; ++a)
; #pragma unroll
;     for (int b = 0; b < 2; ++b)
; #pragma unroll
;       for (int r = 0; r < 16; ++r) acc[a][b][r] = 0.f;
; }
; DI void tile_ffn2(const Params& p, int l, const Chunk& ck, int tile, int next, PF& pf, char* smem) {
;   float* Cs = (float*)smem;
;   const int tid = TID(); const int mi = tile & (MTN - 1), ni = tile >> MTS; const int m0 = mi * 128, n0 = ni * 128;
;   f32x16 acc[2][2]; zero_acc(acc);
;   { const u16* Ap; const u16* Wt; ffn2_ptrs(p, l, tile, Ap, Wt); gemm_run<64>(pf, Ap, 4096, Wt, acc, smem); }
.LBB1_206:
	s_add_i32 s25, s26, s78
	s_cmpk_gt_i32 s25, 0x1ff
	s_cselect_b64 s[28:29], -1, 0
	s_cmpk_lt_i32 s25, 0x200
	s_cselect_b32 s0, s25, -1
	s_and_b32 s16, s41, 0x3f80000
	s_and_b32 s36, s26, 0xffffff80
	s_add_i32 s26, s26, s36
	s_lshl_b32 s36, s36, 1
	s_lshl_b32 s16, s16, 1
	s_add_u32 vcc_lo, s17, s16
	v_mov_b32_e32 v0, v172
	s_addc_u32 vcc_hi, s27, 0
	s_ashr_i32 s37, s36, 31
	s_lshl_b64 s[30:31], s[36:37], 6
	s_add_u32 s30, s34, s30
	s_addc_u32 s31, s40, s31
	s_setprio 0
	s_waitcnt lgkmcnt(0)
	s_lshr_b32 s16, s16, 7
	s_add_u32 s42, s17, s16
	s_addc_u32 s43, s27, 0
	v_and_b32_e32 v174, 63, v172
	v_lshrrev_b32_e32 v175, 6, v172
	v_bfe_u32 v176, v174, 4, 2
	v_lshrrev_b32_e32 v177, 1, v176
	v_xor_b32_e32 v176, v176, v177
	v_and_b32_e32 v176, 1, v176
	v_lshl_or_b32 v176, v176, 1, v177
	v_xor_b32_e32 v176, v176, v174
	v_and_b32_e32 v176, 3, v176
	v_lshlrev_b32_e32 v176, 4, v176
	v_lshrrev_b32_e32 v177, 2, v174
	v_lshl_add_u32 v137, v175, 5, v177
	v_lshl_add_u32 v137, v137, 6, v176
	v_mov_b32_e32 v150, v137
	v_lshl_add_u32 v151, v175, 6, v177
	v_lshl_add_u32 v151, v151, 6, v176
	v_mov_b32_e32 v152, v151
	v_mov_b32_e32 v153, v151
	v_mov_b32_e32 v154, v151
	v_readfirstlane_b32 s16, v175
	s_lshl_b32 s0, s16, 12
	s_lshl_b32 s16, s16, 11
	s_add_u32 s0, s0, 0x2000
	v_bfe_u32 v176, v174, 2, 2
	v_lshrrev_b32_e32 v177, 1, v176
	v_xor_b32_e32 v176, v176, v177
	v_and_b32_e32 v176, 1, v176
	v_lshl_or_b32 v176, v176, 1, v177
	v_lshrrev_b32_e32 v177, 4, v174
	v_xor_b32_e32 v176, v176, v177
	v_lshlrev_b32_e32 v176, 4, v176
	v_and_b32_e32 v174, 15, v174
	v_lshl_add_u32 v174, v174, 6, v176
	v_lshrrev_b32_e32 v176, 1, v175
	v_and_b32_e32 v177, 1, v175
	v_lshl_add_u32 v126, v176, 12, v174
	v_lshl_add_u32 v128, v177, 12, v174
	v_add_u32_e32 v128, 0x2000, v128
	s_barrier
	v_mov_b32_e32 v2, 0
	v_mov_b32_e32 v3, 0
	v_mov_b32_e32 v4, 0
	v_mov_b32_e32 v5, 0
	v_mov_b32_e32 v6, 0
	v_mov_b32_e32 v7, 0
	v_mov_b32_e32 v8, 0
	v_mov_b32_e32 v9, 0
	v_mov_b32_e32 v10, 0
	v_mov_b32_e32 v11, 0
	v_mov_b32_e32 v12, 0
	v_mov_b32_e32 v13, 0
	v_mov_b32_e32 v14, 0
	v_mov_b32_e32 v15, 0
	v_mov_b32_e32 v16, 0
	v_mov_b32_e32 v17, 0
	v_mov_b32_e32 v18, 0
	v_mov_b32_e32 v19, 0
	v_mov_b32_e32 v20, 0
	v_mov_b32_e32 v21, 0
	v_mov_b32_e32 v22, 0
	v_mov_b32_e32 v23, 0
	v_mov_b32_e32 v24, 0
	v_mov_b32_e32 v25, 0
	v_mov_b32_e32 v26, 0
	v_mov_b32_e32 v27, 0
	v_mov_b32_e32 v28, 0
	v_mov_b32_e32 v29, 0
	v_mov_b32_e32 v30, 0
	v_mov_b32_e32 v31, 0
	v_mov_b32_e32 v32, 0
	v_mov_b32_e32 v33, 0
	v_mov_b32_e32 v34, 0
	v_mov_b32_e32 v35, 0
	v_mov_b32_e32 v36, 0
	v_mov_b32_e32 v37, 0
	v_mov_b32_e32 v38, 0
	v_mov_b32_e32 v39, 0
	v_mov_b32_e32 v40, 0
	v_mov_b32_e32 v41, 0
	v_mov_b32_e32 v42, 0
	v_mov_b32_e32 v43, 0
	v_mov_b32_e32 v44, 0
	v_mov_b32_e32 v45, 0
	v_mov_b32_e32 v46, 0
	v_mov_b32_e32 v47, 0
	v_mov_b32_e32 v48, 0
	v_mov_b32_e32 v49, 0
	v_mov_b32_e32 v50, 0
	v_mov_b32_e32 v51, 0
	v_mov_b32_e32 v52, 0
	v_mov_b32_e32 v53, 0
	v_mov_b32_e32 v54, 0
	v_mov_b32_e32 v55, 0
	v_mov_b32_e32 v56, 0
	v_mov_b32_e32 v57, 0
	v_mov_b32_e32 v58, 0
	v_mov_b32_e32 v59, 0
	v_mov_b32_e32 v60, 0
	v_mov_b32_e32 v61, 0
	v_mov_b32_e32 v62, 0
	v_mov_b32_e32 v63, 0
	v_mov_b32_e32 v64, 0
	v_mov_b32_e32 v65, 0
	v_mov_b32_e32 v74, 0
	v_mov_b32_e32 v75, 0
	v_mov_b32_e32 v76, 0
	v_mov_b32_e32 v77, 0
	v_mov_b32_e32 v78, 0
	v_mov_b32_e32 v79, 0
	v_mov_b32_e32 v80, 0
	v_mov_b32_e32 v81, 0
	v_mov_b32_e32 v82, 0
	v_mov_b32_e32 v83, 0
	v_mov_b32_e32 v84, 0
	v_mov_b32_e32 v85, 0
	v_mov_b32_e32 v86, 0
	v_mov_b32_e32 v87, 0
	v_mov_b32_e32 v88, 0
	v_mov_b32_e32 v89, 0
	v_mov_b32_e32 v90, 0
	v_mov_b32_e32 v91, 0
	v_mov_b32_e32 v92, 0
	v_mov_b32_e32 v93, 0
	v_mov_b32_e32 v94, 0
	v_mov_b32_e32 v95, 0
	v_mov_b32_e32 v96, 0
	v_mov_b32_e32 v97, 0
	v_mov_b32_e32 v98, 0
	v_mov_b32_e32 v99, 0
	v_mov_b32_e32 v100, 0
	v_mov_b32_e32 v101, 0
	v_mov_b32_e32 v102, 0
	v_mov_b32_e32 v103, 0
	v_mov_b32_e32 v104, 0
	v_mov_b32_e32 v105, 0
	v_mov_b32_e32 v106, 0
	v_mov_b32_e32 v107, 0
	v_mov_b32_e32 v108, 0
	v_mov_b32_e32 v109, 0
	v_mov_b32_e32 v110, 0
	v_mov_b32_e32 v111, 0
	v_mov_b32_e32 v112, 0
	v_mov_b32_e32 v113, 0
	v_mov_b32_e32 v114, 0
	v_mov_b32_e32 v115, 0
	v_mov_b32_e32 v116, 0
	v_mov_b32_e32 v117, 0
	v_mov_b32_e32 v118, 0
	v_mov_b32_e32 v119, 0
	v_mov_b32_e32 v120, 0
	v_mov_b32_e32 v121, 0
	v_mov_b32_e32 v208, 0
	v_mov_b32_e32 v209, 0
	v_mov_b32_e32 v210, 0
	v_mov_b32_e32 v211, 0
	v_mov_b32_e32 v212, 0
	v_mov_b32_e32 v213, 0
	v_mov_b32_e32 v214, 0
	v_mov_b32_e32 v215, 0
	v_mov_b32_e32 v216, 0
	v_mov_b32_e32 v217, 0
	v_mov_b32_e32 v218, 0
	v_mov_b32_e32 v219, 0
	v_mov_b32_e32 v220, 0
	v_mov_b32_e32 v221, 0
	v_mov_b32_e32 v222, 0
	v_mov_b32_e32 v223, 0
	s_add_u32 m0, s16, 0x0
	s_nop 0
	global_load_lds_dwordx4 v137, s[42:43]
	global_load_lds_dwordx4 v150, s[42:43] offset:1024
	s_add_u32 m0, s0, 0x0
	s_nop 0
	global_load_lds_dwordx4 v151, s[30:31]
	global_load_lds_dwordx4 v152, s[30:31] offset:1024
	global_load_lds_dwordx4 v153, s[30:31] offset:2048
	global_load_lds_dwordx4 v154, s[30:31] offset:3072
	s_add_u32 m0, s16, 0x6000
	s_add_u32 s42, s42, 0x100000
	s_addc_u32 s43, s43, 0
	global_load_lds_dwordx4 v137, s[42:43]
	global_load_lds_dwordx4 v150, s[42:43] offset:1024
	s_add_u32 m0, s0, 0x6000
	s_add_u32 s30, s30, 0x10000
	s_addc_u32 s31, s31, 0
	global_load_lds_dwordx4 v151, s[30:31]
	global_load_lds_dwordx4 v152, s[30:31] offset:1024
	global_load_lds_dwordx4 v153, s[30:31] offset:2048
	global_load_lds_dwordx4 v154, s[30:31] offset:3072
	s_mov_b32 s46, 42
; #define BLOAD(A_, B_, kt) do { _Pragma("unroll") for (int i = 0; i < 4; ++i) { \
;     A_[i] = *(const u32x4*)((const char*)Ap + (aoff + (unsigned)(32 * i * lda + (kt) * 64) * 2u)); B_[i] = *(const u32x4*)((const char*)Wt + (woff + (unsigned)(32 * i * K + (kt) * 64) * 2u)); } } while (0)
; #define BLOAD(A_, B_, kt) do { _Pragma("unroll") for (int i = 0; i < 4; ++i) { \
;     A_[i] = *(const u32x4*)((const char*)Ap + (aoff + (unsigned)(32 * i * lda + (kt) * 64) * 2u)); B_[i] = *(const u32x4*)((const char*)Wt + (woff + (unsigned)(32 * i * K + (kt) * 64) * 2u)); } } while (0)
; #define BSTORE(A_, B_, buf) do { _Pragma("unroll") for (int i = 0; i < 4; ++i) { \
;     *(u32x4*)&As[(buf) * GBUF + (srow + 32 * i) * LDT + sc8] = A_[i]; \
;     *(u32x4*)&Bs[(buf) * GBUF + (srow + 32 * i) * LDT + sc8] = B_[i]; } } while (0)
; template <int NK>
; DI void gemm_run(PF& pf, const u16* __restrict__ Ap, int lda, const u16* __restrict__ Wt, f32x16 (&acc)[2][2], char* smem) {
;     ...
;   __builtin_amdgcn_s_setprio(0);
;   __syncthreads();
;   BSTORE(pf.a0, pf.b0, 0);
;   BLOAD(pf.a0, pf.b0, 2);
;   __syncthreads();
; #pragma unroll
;   for (int kt = 0; kt < nk; kt += 2) {
;     BCOMP(0);
;     BSTORE(pf.a1, pf.b1, 1);
;     if (kt + 3 < nk) BLOAD(pf.a1, pf.b1, kt + 3);
;     __syncthreads();
;     BCOMP(1);
;     if (kt + 2 < nk) { BSTORE(pf.a0, pf.b0, 0); if (kt + 4 < nk) BLOAD(pf.a0, pf.b0, kt + 4); }
;     __syncthreads();
.Lffn2_kloop:
	s_waitcnt vmcnt(6)
	s_barrier
	s_setprio 1
	ds_read_b128 v[224:227], v126 offset:0
	ds_read_b128 v[240:243], v128 offset:0
	ds_read_b128 v[244:247], v128 offset:1024
	ds_read_b128 v[248:251], v128 offset:2048
	ds_read_b128 v[156:159], v128 offset:3072
	ds_read_b128 v[228:231], v126 offset:1024
	ds_read_b128 v[232:235], v126 offset:2048
	ds_read_b128 v[236:239], v126 offset:3072
	ds_read_b128 v[160:163], v128 offset:8192
	ds_read_b128 v[164:167], v128 offset:9216
	ds_read_b128 v[168:171], v128 offset:10240
	ds_read_b128 v[122:125], v128 offset:11264
	s_add_u32 m0, s16, 0xc000
	s_add_u32 s42, s42, 0x100000
	s_addc_u32 s43, s43, 0
	global_load_lds_dwordx4 v137, s[42:43]
	global_load_lds_dwordx4 v150, s[42:43] offset:1024
	s_add_u32 m0, s0, 0xc000
	s_add_u32 s30, s30, 0x10000
	s_addc_u32 s31, s31, 0
	global_load_lds_dwordx4 v151, s[30:31]
	global_load_lds_dwordx4 v152, s[30:31] offset:1024
	global_load_lds_dwordx4 v153, s[30:31] offset:2048
	global_load_lds_dwordx4 v154, s[30:31] offset:3072
	s_waitcnt lgkmcnt(10)
	v_mfma_f32_16x16x32_bf16 v[2:5], v[224:227], v[240:243], v[2:5]
	s_waitcnt lgkmcnt(9)
	v_mfma_f32_16x16x32_bf16 v[6:9], v[224:227], v[244:247], v[6:9]
	s_waitcnt lgkmcnt(8)
	v_mfma_f32_16x16x32_bf16 v[10:13], v[224:227], v[248:251], v[10:13]
	s_waitcnt lgkmcnt(7)
	v_mfma_f32_16x16x32_bf16 v[14:17], v[224:227], v[156:159], v[14:17]
	s_waitcnt lgkmcnt(6)
	v_mfma_f32_16x16x32_bf16 v[18:21], v[228:231], v[240:243], v[18:21]
	v_mfma_f32_16x16x32_bf16 v[22:25], v[228:231], v[244:247], v[22:25]
	v_mfma_f32_16x16x32_bf16 v[26:29], v[228:231], v[248:251], v[26:29]
	v_mfma_f32_16x16x32_bf16 v[30:33], v[228:231], v[156:159], v[30:33]
	s_waitcnt lgkmcnt(5)
	v_mfma_f32_16x16x32_bf16 v[34:37], v[232:235], v[240:243], v[34:37]
	v_mfma_f32_16x16x32_bf16 v[38:41], v[232:235], v[244:247], v[38:41]
	v_mfma_f32_16x16x32_bf16 v[42:45], v[232:235], v[248:251], v[42:45]
	v_mfma_f32_16x16x32_bf16 v[46:49], v[232:235], v[156:159], v[46:49]
	s_waitcnt lgkmcnt(4)
	v_mfma_f32_16x16x32_bf16 v[50:53], v[236:239], v[240:243], v[50:53]
	v_mfma_f32_16x16x32_bf16 v[54:57], v[236:239], v[244:247], v[54:57]
	v_mfma_f32_16x16x32_bf16 v[58:61], v[236:239], v[248:251], v[58:61]
	v_mfma_f32_16x16x32_bf16 v[62:65], v[236:239], v[156:159], v[62:65]
	s_waitcnt lgkmcnt(3)
	v_mfma_f32_16x16x32_bf16 v[74:77], v[224:227], v[160:163], v[74:77]
	s_waitcnt lgkmcnt(2)
	v_mfma_f32_16x16x32_bf16 v[78:81], v[224:227], v[164:167], v[78:81]
	s_waitcnt lgkmcnt(1)
	v_mfma_f32_16x16x32_bf16 v[82:85], v[224:227], v[168:171], v[82:85]
	s_waitcnt lgkmcnt(0)
	v_mfma_f32_16x16x32_bf16 v[86:89], v[224:227], v[122:125], v[86:89]
	v_mfma_f32_16x16x32_bf16 v[90:93], v[228:231], v[160:163], v[90:93]
	v_mfma_f32_16x16x32_bf16 v[94:97], v[228:231], v[164:167], v[94:97]
	v_mfma_f32_16x16x32_bf16 v[98:101], v[228:231], v[168:171], v[98:101]
	v_mfma_f32_16x16x32_bf16 v[102:105], v[228:231], v[122:125], v[102:105]
	v_mfma_f32_16x16x32_bf16 v[106:109], v[232:235], v[160:163], v[106:109]
	v_mfma_f32_16x16x32_bf16 v[110:113], v[232:235], v[164:167], v[110:113]
	v_mfma_f32_16x16x32_bf16 v[114:117], v[232:235], v[168:171], v[114:117]
	v_mfma_f32_16x16x32_bf16 v[118:121], v[232:235], v[122:125], v[118:121]
	v_mfma_f32_16x16x32_bf16 v[208:211], v[236:239], v[160:163], v[208:211]
	v_mfma_f32_16x16x32_bf16 v[212:215], v[236:239], v[164:167], v[212:215]
	v_mfma_f32_16x16x32_bf16 v[216:219], v[236:239], v[168:171], v[216:219]
	v_mfma_f32_16x16x32_bf16 v[220:223], v[236:239], v[122:125], v[220:223]
	s_setprio 0
	s_waitcnt vmcnt(6)
	s_barrier
	s_setprio 1
	ds_read_b128 v[224:227], v126 offset:24576
	ds_read_b128 v[240:243], v128 offset:24576
	ds_read_b128 v[244:247], v128 offset:25600
	ds_read_b128 v[248:251], v128 offset:26624
	ds_read_b128 v[156:159], v128 offset:27648
	ds_read_b128 v[228:231], v126 offset:25600
	ds_read_b128 v[232:235], v126 offset:26624
	ds_read_b128 v[236:239], v126 offset:27648
	ds_read_b128 v[160:163], v128 offset:32768
	ds_read_b128 v[164:167], v128 offset:33792
	ds_read_b128 v[168:171], v128 offset:34816
	ds_read_b128 v[122:125], v128 offset:35840
	s_add_u32 m0, s16, 0x0
	s_add_u32 s42, s42, 0x100000
	s_addc_u32 s43, s43, 0
	global_load_lds_dwordx4 v137, s[42:43]
	global_load_lds_dwordx4 v150, s[42:43] offset:1024
	s_add_u32 m0, s0, 0x0
	s_add_u32 s30, s30, 0x10000
	s_addc_u32 s31, s31, 0
	global_load_lds_dwordx4 v151, s[30:31]
	global_load_lds_dwordx4 v152, s[30:31] offset:1024
	global_load_lds_dwordx4 v153, s[30:31] offset:2048
	global_load_lds_dwordx4 v154, s[30:31] offset:3072
	s_waitcnt lgkmcnt(10)
	v_mfma_f32_16x16x32_bf16 v[2:5], v[224:227], v[240:243], v[2:5]
	s_waitcnt lgkmcnt(9)
	v_mfma_f32_16x16x32_bf16 v[6:9], v[224:227], v[244:247], v[6:9]
	s_waitcnt lgkmcnt(8)
	v_mfma_f32_16x16x32_bf16 v[10:13], v[224:227], v[248:251], v[10:13]
	s_waitcnt lgkmcnt(7)
	v_mfma_f32_16x16x32_bf16 v[14:17], v[224:227], v[156:159], v[14:17]
	s_waitcnt lgkmcnt(6)
	v_mfma_f32_16x16x32_bf16 v[18:21], v[228:231], v[240:243], v[18:21]
	v_mfma_f32_16x16x32_bf16 v[22:25], v[228:231], v[244:247], v[22:25]
	v_mfma_f32_16x16x32_bf16 v[26:29], v[228:231], v[248:251], v[26:29]
	v_mfma_f32_16x16x32_bf16 v[30:33], v[228:231], v[156:159], v[30:33]
	s_waitcnt lgkmcnt(5)
	v_mfma_f32_16x16x32_bf16 v[34:37], v[232:235], v[240:243], v[34:37]
	v_mfma_f32_16x16x32_bf16 v[38:41], v[232:235], v[244:247], v[38:41]
	v_mfma_f32_16x16x32_bf16 v[42:45], v[232:235], v[248:251], v[42:45]
	v_mfma_f32_16x16x32_bf16 v[46:49], v[232:235], v[156:159], v[46:49]
	s_waitcnt lgkmcnt(4)
; #define BLOAD(A_, B_, kt) do { _Pragma("unroll") for (int i = 0; i < 4; ++i) { \
;     A_[i] = *(const u32x4*)((const char*)Ap + (aoff + (unsigned)(32 * i * lda + (kt) * 64) * 2u)); B_[i] = *(const u32x4*)((const char*)Wt + (woff + (unsigned)(32 * i * K + (kt) * 64) * 2u)); } } while (0)
; #define BLOAD(A_, B_, kt) do { _Pragma("unroll") for (int i = 0; i < 4; ++i) { \
;     A_[i] = *(const u32x4*)((const char*)Ap + (aoff + (unsigned)(32 * i * lda + (kt) * 64) * 2u)); B_[i] = *(const u32x4*)((const char*)Wt + (woff + (unsigned)(32 * i * K + (kt) * 64) * 2u)); } } while (0)
; #define BSTORE(A_, B_, buf) do { _Pragma("unroll") for (int i = 0; i < 4; ++i) { \
;     *(u32x4*)&As[(buf) * GBUF + (srow + 32 * i) * LDT + sc8] = A_[i]; \
;     *(u32x4*)&Bs[(buf) * GBUF + (srow + 32 * i) * LDT + sc8] = B_[i]; } } while (0)
; template <int NK>
; DI void gemm_run(PF& pf, const u16* __restrict__ Ap, int lda, const u16* __restrict__ Wt, f32x16 (&acc)[2][2], char* smem) {
;     ...
;   __builtin_amdgcn_s_setprio(0);
;   __syncthreads();
;   BSTORE(pf.a0, pf.b0, 0);
;   BLOAD(pf.a0, pf.b0, 2);
;   __syncthreads();
; #pragma unroll
;   for (int kt = 0; kt < nk; kt += 2) {
;     BCOMP(0);
;     BSTORE(pf.a1, pf.b1, 1);
;     if (kt + 3 < nk) BLOAD(pf.a1, pf.b1, kt + 3);
;     __syncthreads();
;     BCOMP(1);
;     if (kt + 2 < nk) { BSTORE(pf.a0, pf.b0, 0); if (kt + 4 < nk) BLOAD(pf.a0, pf.b0, kt + 4); }
;     __syncthreads();
	v_mfma_f32_16x16x32_bf16 v[50:53], v[236:239], v[240:243], v[50:53]
	v_mfma_f32_16x16x32_bf16 v[54:57], v[236:239], v[244:247], v[54:57]
	v_mfma_f32_16x16x32_bf16 v[58:61], v[236:239], v[248:251], v[58:61]
	v_mfma_f32_16x16x32_bf16 v[62:65], v[236:239], v[156:159], v[62:65]
	s_waitcnt lgkmcnt(3)
	v_mfma_f32_16x16x32_bf16 v[74:77], v[224:227], v[160:163], v[74:77]
	s_waitcnt lgkmcnt(2)
	v_mfma_f32_16x16x32_bf16 v[78:81], v[224:227], v[164:167], v[78:81]
	s_waitcnt lgkmcnt(1)
	v_mfma_f32_16x16x32_bf16 v[82:85], v[224:227], v[168:171], v[82:85]
	s_waitcnt lgkmcnt(0)
	v_mfma_f32_16x16x32_bf16 v[86:89], v[224:227], v[122:125], v[86:89]
	v_mfma_f32_16x16x32_bf16 v[90:93], v[228:231], v[160:163], v[90:93]
	v_mfma_f32_16x16x32_bf16 v[94:97], v[228:231], v[164:167], v[94:97]
	v_mfma_f32_16x16x32_bf16 v[98:101], v[228:231], v[168:171], v[98:101]
	v_mfma_f32_16x16x32_bf16 v[102:105], v[228:231], v[122:125], v[102:105]
	v_mfma_f32_16x16x32_bf16 v[106:109], v[232:235], v[160:163], v[106:109]
	v_mfma_f32_16x16x32_bf16 v[110:113], v[232:235], v[164:167], v[110:113]
	v_mfma_f32_16x16x32_bf16 v[114:117], v[232:235], v[168:171], v[114:117]
	v_mfma_f32_16x16x32_bf16 v[118:121], v[232:235], v[122:125], v[118:121]
	v_mfma_f32_16x16x32_bf16 v[208:211], v[236:239], v[160:163], v[208:211]
	v_mfma_f32_16x16x32_bf16 v[212:215], v[236:239], v[164:167], v[212:215]
	v_mfma_f32_16x16x32_bf16 v[216:219], v[236:239], v[168:171], v[216:219]
	v_mfma_f32_16x16x32_bf16 v[220:223], v[236:239], v[122:125], v[220:223]
	s_setprio 0
	s_waitcnt vmcnt(6)
	s_barrier
	s_setprio 1
	ds_read_b128 v[224:227], v126 offset:49152
	ds_read_b128 v[240:243], v128 offset:49152
	ds_read_b128 v[244:247], v128 offset:50176
	ds_read_b128 v[248:251], v128 offset:51200
	ds_read_b128 v[156:159], v128 offset:52224
	ds_read_b128 v[228:231], v126 offset:50176
	ds_read_b128 v[232:235], v126 offset:51200
	ds_read_b128 v[236:239], v126 offset:52224
	ds_read_b128 v[160:163], v128 offset:57344
	ds_read_b128 v[164:167], v128 offset:58368
	ds_read_b128 v[168:171], v128 offset:59392
	ds_read_b128 v[122:125], v128 offset:60416
	s_add_u32 m0, s16, 0x6000
	s_add_u32 s42, s42, 0x100000
	s_addc_u32 s43, s43, 0
	global_load_lds_dwordx4 v137, s[42:43]
	global_load_lds_dwordx4 v150, s[42:43] offset:1024
	s_add_u32 m0, s0, 0x6000
	s_add_u32 s30, s30, 0x10000
	s_addc_u32 s31, s31, 0
	global_load_lds_dwordx4 v151, s[30:31]
	global_load_lds_dwordx4 v152, s[30:31] offset:1024
	global_load_lds_dwordx4 v153, s[30:31] offset:2048
	global_load_lds_dwordx4 v154, s[30:31] offset:3072
	s_waitcnt lgkmcnt(10)
	v_mfma_f32_16x16x32_bf16 v[2:5], v[224:227], v[240:243], v[2:5]
	s_waitcnt lgkmcnt(9)
	v_mfma_f32_16x16x32_bf16 v[6:9], v[224:227], v[244:247], v[6:9]
	s_waitcnt lgkmcnt(8)
	v_mfma_f32_16x16x32_bf16 v[10:13], v[224:227], v[248:251], v[10:13]
	s_waitcnt lgkmcnt(7)
	v_mfma_f32_16x16x32_bf16 v[14:17], v[224:227], v[156:159], v[14:17]
	s_waitcnt lgkmcnt(6)
	v_mfma_f32_16x16x32_bf16 v[18:21], v[228:231], v[240:243], v[18:21]
	v_mfma_f32_16x16x32_bf16 v[22:25], v[228:231], v[244:247], v[22:25]
	v_mfma_f32_16x16x32_bf16 v[26:29], v[228:231], v[248:251], v[26:29]
	v_mfma_f32_16x16x32_bf16 v[30:33], v[228:231], v[156:159], v[30:33]
	s_waitcnt lgkmcnt(5)
	v_mfma_f32_16x16x32_bf16 v[34:37], v[232:235], v[240:243], v[34:37]
	v_mfma_f32_16x16x32_bf16 v[38:41], v[232:235], v[244:247], v[38:41]
	v_mfma_f32_16x16x32_bf16 v[42:45], v[232:235], v[248:251], v[42:45]
	v_mfma_f32_16x16x32_bf16 v[46:49], v[232:235], v[156:159], v[46:49]
	s_waitcnt lgkmcnt(4)
	v_mfma_f32_16x16x32_bf16 v[50:53], v[236:239], v[240:243], v[50:53]
	v_mfma_f32_16x16x32_bf16 v[54:57], v[236:239], v[244:247], v[54:57]
	v_mfma_f32_16x16x32_bf16 v[58:61], v[236:239], v[248:251], v[58:61]
	v_mfma_f32_16x16x32_bf16 v[62:65], v[236:239], v[156:159], v[62:65]
	s_waitcnt lgkmcnt(3)
	v_mfma_f32_16x16x32_bf16 v[74:77], v[224:227], v[160:163], v[74:77]
	s_waitcnt lgkmcnt(2)
	v_mfma_f32_16x16x32_bf16 v[78:81], v[224:227], v[164:167], v[78:81]
	s_waitcnt lgkmcnt(1)
	v_mfma_f32_16x16x32_bf16 v[82:85], v[224:227], v[168:171], v[82:85]
	s_waitcnt lgkmcnt(0)
	v_mfma_f32_16x16x32_bf16 v[86:89], v[224:227], v[122:125], v[86:89]
	v_mfma_f32_16x16x32_bf16 v[90:93], v[228:231], v[160:163], v[90:93]
	v_mfma_f32_16x16x32_bf16 v[94:97], v[228:231], v[164:167], v[94:97]
	v_mfma_f32_16x16x32_bf16 v[98:101], v[228:231], v[168:171], v[98:101]
	v_mfma_f32_16x16x32_bf16 v[102:105], v[228:231], v[122:125], v[102:105]
	v_mfma_f32_16x16x32_bf16 v[106:109], v[232:235], v[160:163], v[106:109]
	v_mfma_f32_16x16x32_bf16 v[110:113], v[232:235], v[164:167], v[110:113]
	v_mfma_f32_16x16x32_bf16 v[114:117], v[232:235], v[168:171], v[114:117]
	v_mfma_f32_16x16x32_bf16 v[118:121], v[232:235], v[122:125], v[118:121]
	v_mfma_f32_16x16x32_bf16 v[208:211], v[236:239], v[160:163], v[208:211]
	v_mfma_f32_16x16x32_bf16 v[212:215], v[236:239], v[164:167], v[212:215]
	v_mfma_f32_16x16x32_bf16 v[216:219], v[236:239], v[168:171], v[216:219]
	v_mfma_f32_16x16x32_bf16 v[220:223], v[236:239], v[122:125], v[220:223]
	s_setprio 0
	s_sub_u32 s46, s46, 1
	s_cmp_lg_u32 s46, 0
	s_cbranch_scc1 .Lffn2_kloop
	s_waitcnt vmcnt(6)
	s_barrier
; #define BLOAD(A_, B_, kt) do { _Pragma("unroll") for (int i = 0; i < 4; ++i) { \
;     A_[i] = *(const u32x4*)((const char*)Ap + (aoff + (unsigned)(32 * i * lda + (kt) * 64) * 2u)); B_[i] = *(const u32x4*)((const char*)Wt + (woff + (unsigned)(32 * i * K + (kt) * 64) * 2u)); } } while (0)
; #define BLOAD(A_, B_, kt) do { _Pragma("unroll") for (int i = 0; i < 4; ++i) { \
;     A_[i] = *(const u32x4*)((const char*)Ap + (aoff + (unsigned)(32 * i * lda + (kt) * 64) * 2u)); B_[i] = *(const u32x4*)((const char*)Wt + (woff + (unsigned)(32 * i * K + (kt) * 64) * 2u)); } } while (0)
; #define BSTORE(A_, B_, buf) do { _Pragma("unroll") for (int i = 0; i < 4; ++i) { \
;     *(u32x4*)&As[(buf) * GBUF + (srow + 32 * i) * LDT + sc8] = A_[i]; \
;     *(u32x4*)&Bs[(buf) * GBUF + (srow + 32 * i) * LDT + sc8] = B_[i]; } } while (0)
; template <int NK>
; DI void gemm_run(PF& pf, const u16* __restrict__ Ap, int lda, const u16* __restrict__ Wt, f32x16 (&acc)[2][2], char* smem) {
;     ...
;   __builtin_amdgcn_s_setprio(0);
;   __syncthreads();
;   BSTORE(pf.a0, pf.b0, 0);
;   BLOAD(pf.a0, pf.b0, 2);
;   __syncthreads();
; #pragma unroll
;   for (int kt = 0; kt < nk; kt += 2) {
;     BCOMP(0);
;     BSTORE(pf.a1, pf.b1, 1);
;     if (kt + 3 < nk) BLOAD(pf.a1, pf.b1, kt + 3);
;     __syncthreads();
;     BCOMP(1);
;     if (kt + 2 < nk) { BSTORE(pf.a0, pf.b0, 0); if (kt + 4 < nk) BLOAD(pf.a0, pf.b0, kt + 4); }
;     __syncthreads();
	s_setprio 1
	ds_read_b128 v[224:227], v126 offset:0
	ds_read_b128 v[240:243], v128 offset:0
	ds_read_b128 v[244:247], v128 offset:1024
	ds_read_b128 v[248:251], v128 offset:2048
	ds_read_b128 v[156:159], v128 offset:3072
	ds_read_b128 v[228:231], v126 offset:1024
	ds_read_b128 v[232:235], v126 offset:2048
	ds_read_b128 v[236:239], v126 offset:3072
	ds_read_b128 v[160:163], v128 offset:8192
	ds_read_b128 v[164:167], v128 offset:9216
	ds_read_b128 v[168:171], v128 offset:10240
	ds_read_b128 v[122:125], v128 offset:11264
	s_waitcnt lgkmcnt(10)
	v_mfma_f32_16x16x32_bf16 v[2:5], v[224:227], v[240:243], v[2:5]
	s_waitcnt lgkmcnt(9)
	v_mfma_f32_16x16x32_bf16 v[6:9], v[224:227], v[244:247], v[6:9]
	s_waitcnt lgkmcnt(8)
	v_mfma_f32_16x16x32_bf16 v[10:13], v[224:227], v[248:251], v[10:13]
	s_waitcnt lgkmcnt(7)
	v_mfma_f32_16x16x32_bf16 v[14:17], v[224:227], v[156:159], v[14:17]
	s_waitcnt lgkmcnt(6)
	v_mfma_f32_16x16x32_bf16 v[18:21], v[228:231], v[240:243], v[18:21]
	v_mfma_f32_16x16x32_bf16 v[22:25], v[228:231], v[244:247], v[22:25]
	v_mfma_f32_16x16x32_bf16 v[26:29], v[228:231], v[248:251], v[26:29]
	v_mfma_f32_16x16x32_bf16 v[30:33], v[228:231], v[156:159], v[30:33]
	s_waitcnt lgkmcnt(5)
	v_mfma_f32_16x16x32_bf16 v[34:37], v[232:235], v[240:243], v[34:37]
	v_mfma_f32_16x16x32_bf16 v[38:41], v[232:235], v[244:247], v[38:41]
	v_mfma_f32_16x16x32_bf16 v[42:45], v[232:235], v[248:251], v[42:45]
	v_mfma_f32_16x16x32_bf16 v[46:49], v[232:235], v[156:159], v[46:49]
	s_waitcnt lgkmcnt(4)
	v_mfma_f32_16x16x32_bf16 v[50:53], v[236:239], v[240:243], v[50:53]
	v_mfma_f32_16x16x32_bf16 v[54:57], v[236:239], v[244:247], v[54:57]
	v_mfma_f32_16x16x32_bf16 v[58:61], v[236:239], v[248:251], v[58:61]
	v_mfma_f32_16x16x32_bf16 v[62:65], v[236:239], v[156:159], v[62:65]
	s_waitcnt lgkmcnt(3)
	v_mfma_f32_16x16x32_bf16 v[74:77], v[224:227], v[160:163], v[74:77]
	s_waitcnt lgkmcnt(2)
	v_mfma_f32_16x16x32_bf16 v[78:81], v[224:227], v[164:167], v[78:81]
	s_waitcnt lgkmcnt(1)
	v_mfma_f32_16x16x32_bf16 v[82:85], v[224:227], v[168:171], v[82:85]
	s_waitcnt lgkmcnt(0)
	v_mfma_f32_16x16x32_bf16 v[86:89], v[224:227], v[122:125], v[86:89]
	v_mfma_f32_16x16x32_bf16 v[90:93], v[228:231], v[160:163], v[90:93]
	v_mfma_f32_16x16x32_bf16 v[94:97], v[228:231], v[164:167], v[94:97]
	v_mfma_f32_16x16x32_bf16 v[98:101], v[228:231], v[168:171], v[98:101]
	v_mfma_f32_16x16x32_bf16 v[102:105], v[228:231], v[122:125], v[102:105]
	v_mfma_f32_16x16x32_bf16 v[106:109], v[232:235], v[160:163], v[106:109]
	v_mfma_f32_16x16x32_bf16 v[110:113], v[232:235], v[164:167], v[110:113]
	v_mfma_f32_16x16x32_bf16 v[114:117], v[232:235], v[168:171], v[114:117]
	v_mfma_f32_16x16x32_bf16 v[118:121], v[232:235], v[122:125], v[118:121]
	v_mfma_f32_16x16x32_bf16 v[208:211], v[236:239], v[160:163], v[208:211]
	v_mfma_f32_16x16x32_bf16 v[212:215], v[236:239], v[164:167], v[212:215]
	v_mfma_f32_16x16x32_bf16 v[216:219], v[236:239], v[168:171], v[216:219]
	v_mfma_f32_16x16x32_bf16 v[220:223], v[236:239], v[122:125], v[220:223]
	s_setprio 0
	s_waitcnt vmcnt(0)
	s_barrier
	s_setprio 1
	ds_read_b128 v[224:227], v126 offset:24576
	ds_read_b128 v[240:243], v128 offset:24576
	ds_read_b128 v[244:247], v128 offset:25600
	ds_read_b128 v[248:251], v128 offset:26624
	ds_read_b128 v[156:159], v128 offset:27648
	ds_read_b128 v[228:231], v126 offset:25600
	ds_read_b128 v[232:235], v126 offset:26624
	ds_read_b128 v[236:239], v126 offset:27648
	ds_read_b128 v[160:163], v128 offset:32768
	ds_read_b128 v[164:167], v128 offset:33792
	ds_read_b128 v[168:171], v128 offset:34816
	ds_read_b128 v[122:125], v128 offset:35840
	s_waitcnt lgkmcnt(10)
	v_mfma_f32_16x16x32_bf16 v[2:5], v[224:227], v[240:243], v[2:5]
	s_waitcnt lgkmcnt(9)
	v_mfma_f32_16x16x32_bf16 v[6:9], v[224:227], v[244:247], v[6:9]
	s_waitcnt lgkmcnt(8)
	v_mfma_f32_16x16x32_bf16 v[10:13], v[224:227], v[248:251], v[10:13]
	s_waitcnt lgkmcnt(7)
	v_mfma_f32_16x16x32_bf16 v[14:17], v[224:227], v[156:159], v[14:17]
	s_waitcnt lgkmcnt(6)
	v_mfma_f32_16x16x32_bf16 v[18:21], v[228:231], v[240:243], v[18:21]
	v_mfma_f32_16x16x32_bf16 v[22:25], v[228:231], v[244:247], v[22:25]
	v_mfma_f32_16x16x32_bf16 v[26:29], v[228:231], v[248:251], v[26:29]
	v_mfma_f32_16x16x32_bf16 v[30:33], v[228:231], v[156:159], v[30:33]
	s_waitcnt lgkmcnt(5)
	v_mfma_f32_16x16x32_bf16 v[34:37], v[232:235], v[240:243], v[34:37]
	v_mfma_f32_16x16x32_bf16 v[38:41], v[232:235], v[244:247], v[38:41]
	v_mfma_f32_16x16x32_bf16 v[42:45], v[232:235], v[248:251], v[42:45]
	v_mfma_f32_16x16x32_bf16 v[46:49], v[232:235], v[156:159], v[46:49]
	s_waitcnt lgkmcnt(4)
	v_mfma_f32_16x16x32_bf16 v[50:53], v[236:239], v[240:243], v[50:53]
	v_mfma_f32_16x16x32_bf16 v[54:57], v[236:239], v[244:247], v[54:57]
	v_mfma_f32_16x16x32_bf16 v[58:61], v[236:239], v[248:251], v[58:61]
	v_mfma_f32_16x16x32_bf16 v[62:65], v[236:239], v[156:159], v[62:65]
	s_waitcnt lgkmcnt(3)
	v_mfma_f32_16x16x32_bf16 v[74:77], v[224:227], v[160:163], v[74:77]
	s_waitcnt lgkmcnt(2)
	v_mfma_f32_16x16x32_bf16 v[78:81], v[224:227], v[164:167], v[78:81]
	s_waitcnt lgkmcnt(1)
	v_mfma_f32_16x16x32_bf16 v[82:85], v[224:227], v[168:171], v[82:85]
	s_waitcnt lgkmcnt(0)
	v_mfma_f32_16x16x32_bf16 v[86:89], v[224:227], v[122:125], v[86:89]
	v_mfma_f32_16x16x32_bf16 v[90:93], v[228:231], v[160:163], v[90:93]
	v_mfma_f32_16x16x32_bf16 v[94:97], v[228:231], v[164:167], v[94:97]
	v_mfma_f32_16x16x32_bf16 v[98:101], v[228:231], v[168:171], v[98:101]
	v_mfma_f32_16x16x32_bf16 v[102:105], v[228:231], v[122:125], v[102:105]
	v_mfma_f32_16x16x32_bf16 v[106:109], v[232:235], v[160:163], v[106:109]
	v_mfma_f32_16x16x32_bf16 v[110:113], v[232:235], v[164:167], v[110:113]
	v_mfma_f32_16x16x32_bf16 v[114:117], v[232:235], v[168:171], v[114:117]
	v_mfma_f32_16x16x32_bf16 v[118:121], v[232:235], v[122:125], v[118:121]
	v_mfma_f32_16x16x32_bf16 v[208:211], v[236:239], v[160:163], v[208:211]
	v_mfma_f32_16x16x32_bf16 v[212:215], v[236:239], v[164:167], v[212:215]
	v_mfma_f32_16x16x32_bf16 v[216:219], v[236:239], v[168:171], v[216:219]
	v_mfma_f32_16x16x32_bf16 v[220:223], v[236:239], v[122:125], v[220:223]
	s_setprio 0
	s_barrier
	s_mov_b32 s16, 0
; DI int TID() { int t = (int)__builtin_amdgcn_workitem_id_x(); asm volatile("" : "+v"(t)); return t; }
; DI int crow(int r, int hi) { return (r & 3) + 8 * (r >> 2) + 4 * hi; }
; DI void acc_to_cs(const f32x16 (&acc)[2][2], float* Cs) {
;   __builtin_amdgcn_s_setprio(2);
;   const int tid = TID(), lane = tid & 63, w = tid >> 6, wm = w >> 1, wn = w & 1, r32 = lane & 31, hi = lane >> 5;
; #pragma unroll
;   for (int mt = 0; mt < 2; ++mt)
; #pragma unroll
;     for (int nt = 0; nt < 2; ++nt)
; #pragma unroll
;       for (int r = 0; r < 16; ++r) Cs[(wm * 64 + mt * 32 + crow(r, hi)) * CSL + wn * 64 + nt * 32 + r32] = acc[mt][nt][r];
;   __syncthreads();
; }
.LBB1_208:
.Lffn2_epi2:
	v_and_b32_e32 v224, 63, v172
	v_lshrrev_b32_e32 v225, 6, v172
	v_lshrrev_b32_e32 v226, 4, v224
	v_lshlrev_b32_e32 v226, 2, v226
	v_lshrrev_b32_e32 v227, 1, v225
	v_lshl_add_u32 v226, v227, 6, v226
	v_mul_u32_u24_e32 v226, 0x84, v226
	v_and_b32_e32 v227, 1, v225
	v_and_b32_e32 v224, 15, v224
	v_lshl_add_u32 v224, v227, 6, v224
	v_add_lshl_u32 v226, v226, v224, 2
	s_cmp_lg_u32 s16, 0
	s_cbranch_scc1 .Lffn2_w1
	ds_write_b32 v226, v2 offset:0
	ds_write_b32 v226, v3 offset:528
	ds_write_b32 v226, v4 offset:1056
	ds_write_b32 v226, v5 offset:1584
	ds_write_b32 v226, v6 offset:64
	ds_write_b32 v226, v7 offset:592
	ds_write_b32 v226, v8 offset:1120
	ds_write_b32 v226, v9 offset:1648
	ds_write_b32 v226, v10 offset:128
	ds_write_b32 v226, v11 offset:656
	ds_write_b32 v226, v12 offset:1184
	ds_write_b32 v226, v13 offset:1712
	ds_write_b32 v226, v14 offset:192
	ds_write_b32 v226, v15 offset:720
	ds_write_b32 v226, v16 offset:1248
	ds_write_b32 v226, v17 offset:1776
	ds_write_b32 v226, v18 offset:8448
	ds_write_b32 v226, v19 offset:8976
	ds_write_b32 v226, v20 offset:9504
	ds_write_b32 v226, v21 offset:10032
	ds_write_b32 v226, v22 offset:8512
	ds_write_b32 v226, v23 offset:9040
	ds_write_b32 v226, v24 offset:9568
	ds_write_b32 v226, v25 offset:10096
	ds_write_b32 v226, v26 offset:8576
	ds_write_b32 v226, v27 offset:9104
	ds_write_b32 v226, v28 offset:9632
	ds_write_b32 v226, v29 offset:10160
	ds_write_b32 v226, v30 offset:8640
	ds_write_b32 v226, v31 offset:9168
	ds_write_b32 v226, v32 offset:9696
	ds_write_b32 v226, v33 offset:10224
	ds_write_b32 v226, v34 offset:16896
	ds_write_b32 v226, v35 offset:17424
	ds_write_b32 v226, v36 offset:17952
	ds_write_b32 v226, v37 offset:18480
	ds_write_b32 v226, v38 offset:16960
	ds_write_b32 v226, v39 offset:17488
	ds_write_b32 v226, v40 offset:18016
	ds_write_b32 v226, v41 offset:18544
	ds_write_b32 v226, v42 offset:17024
	ds_write_b32 v226, v43 offset:17552
	ds_write_b32 v226, v44 offset:18080
	ds_write_b32 v226, v45 offset:18608
	ds_write_b32 v226, v46 offset:17088
	ds_write_b32 v226, v47 offset:17616
	ds_write_b32 v226, v48 offset:18144
	ds_write_b32 v226, v49 offset:18672
	ds_write_b32 v226, v50 offset:25344
	ds_write_b32 v226, v51 offset:25872
	ds_write_b32 v226, v52 offset:26400
	ds_write_b32 v226, v53 offset:26928
	ds_write_b32 v226, v54 offset:25408
	ds_write_b32 v226, v55 offset:25936
	ds_write_b32 v226, v56 offset:26464
	ds_write_b32 v226, v57 offset:26992
	ds_write_b32 v226, v58 offset:25472
	ds_write_b32 v226, v59 offset:26000
	ds_write_b32 v226, v60 offset:26528
	ds_write_b32 v226, v61 offset:27056
	ds_write_b32 v226, v62 offset:25536
	ds_write_b32 v226, v63 offset:26064
	ds_write_b32 v226, v64 offset:26592
	ds_write_b32 v226, v65 offset:27120
	s_branch .Lffn2_wd
; DI int TID() { int t = (int)__builtin_amdgcn_workitem_id_x(); asm volatile("" : "+v"(t)); return t; }
; DI u32x4 pack8(const float (&v)[8]) { u32x4 r = {pk2(v[0], v[1]), pk2(v[2], v[3]), pk2(v[4], v[5]), pk2(v[6], v[7])}; return r; }
; DI int crow(int r, int hi) { return (r & 3) + 8 * (r >> 2) + 4 * hi; }
; DI void acc_to_cs(const f32x16 (&acc)[2][2], float* Cs) {
;   __builtin_amdgcn_s_setprio(2);
;   const int tid = TID(), lane = tid & 63, w = tid >> 6, wm = w >> 1, wn = w & 1, r32 = lane & 31, hi = lane >> 5;
; #pragma unroll
;   for (int mt = 0; mt < 2; ++mt)
; #pragma unroll
;     for (int nt = 0; nt < 2; ++nt)
; #pragma unroll
;       for (int r = 0; r < 16; ++r) Cs[(wm * 64 + mt * 32 + crow(r, hi)) * CSL + wn * 64 + nt * 32 + r32] = acc[mt][nt][r];
;   __syncthreads();
; }
; DI void tile_ffn2(const Params& p, int l, const Chunk& ck, int tile, int next, PF& pf, char* smem) {
;     ...
;   const int row = tid >> 1, half = tid & 1; float ssq = 0.f;
;   float* xd = p.out + (size_t)(ck.tok0 + m0 + row) * 1024 + n0 + half * 64;
;   u16* xb = (u16*)(p.ws + OFF_XB) + (size_t)(m0 + row) * 1024 + n0 + half * 64;
; #pragma unroll
;   for (int c8 = 0; c8 < 8; ++c8) {
;     float v[8], x[8]; cs_ld8(Cs, row, half * 64 + c8 * 8, v); unpack8(*(const u32x4*)(xb + c8 * 8), x);
; #pragma unroll
;     for (int j = 0; j < 8; ++j) { v[j] += x[j]; ssq += v[j] * v[j]; }
;     if (l == 0) *(u32x4*)(xb + c8 * 8) = pack8(v);
;     else { *(f32x4*)(xd + c8 * 8) = f32x4{v[0], v[1], v[2], v[3]}; *(f32x4*)(xd + c8 * 8 + 4) = f32x4{v[4], v[5], v[6], v[7]}; }
;   }
.Lffn2_w1:
	ds_write_b32 v226, v74 offset:0
	ds_write_b32 v226, v75 offset:528
	ds_write_b32 v226, v76 offset:1056
	ds_write_b32 v226, v77 offset:1584
	ds_write_b32 v226, v78 offset:64
	ds_write_b32 v226, v79 offset:592
	ds_write_b32 v226, v80 offset:1120
	ds_write_b32 v226, v81 offset:1648
	ds_write_b32 v226, v82 offset:128
	ds_write_b32 v226, v83 offset:656
	ds_write_b32 v226, v84 offset:1184
	ds_write_b32 v226, v85 offset:1712
	ds_write_b32 v226, v86 offset:192
	ds_write_b32 v226, v87 offset:720
	ds_write_b32 v226, v88 offset:1248
	ds_write_b32 v226, v89 offset:1776
	ds_write_b32 v226, v90 offset:8448
	ds_write_b32 v226, v91 offset:8976
	ds_write_b32 v226, v92 offset:9504
	ds_write_b32 v226, v93 offset:10032
	ds_write_b32 v226, v94 offset:8512
	ds_write_b32 v226, v95 offset:9040
	ds_write_b32 v226, v96 offset:9568
	ds_write_b32 v226, v97 offset:10096
	ds_write_b32 v226, v98 offset:8576
	ds_write_b32 v226, v99 offset:9104
	ds_write_b32 v226, v100 offset:9632
	ds_write_b32 v226, v101 offset:10160
	ds_write_b32 v226, v102 offset:8640
	ds_write_b32 v226, v103 offset:9168
	ds_write_b32 v226, v104 offset:9696
	ds_write_b32 v226, v105 offset:10224
	ds_write_b32 v226, v106 offset:16896
	ds_write_b32 v226, v107 offset:17424
	ds_write_b32 v226, v108 offset:17952
	ds_write_b32 v226, v109 offset:18480
	ds_write_b32 v226, v110 offset:16960
	ds_write_b32 v226, v111 offset:17488
	ds_write_b32 v226, v112 offset:18016
	ds_write_b32 v226, v113 offset:18544
	ds_write_b32 v226, v114 offset:17024
	ds_write_b32 v226, v115 offset:17552
	ds_write_b32 v226, v116 offset:18080
	ds_write_b32 v226, v117 offset:18608
	ds_write_b32 v226, v118 offset:17088
	ds_write_b32 v226, v119 offset:17616
	ds_write_b32 v226, v120 offset:18144
	ds_write_b32 v226, v121 offset:18672
	ds_write_b32 v226, v208 offset:25344
	ds_write_b32 v226, v209 offset:25872
	ds_write_b32 v226, v210 offset:26400
	ds_write_b32 v226, v211 offset:26928
	ds_write_b32 v226, v212 offset:25408
	ds_write_b32 v226, v213 offset:25936
	ds_write_b32 v226, v214 offset:26464
	ds_write_b32 v226, v215 offset:26992
	ds_write_b32 v226, v216 offset:25472
	ds_write_b32 v226, v217 offset:26000
	ds_write_b32 v226, v218 offset:26528
	ds_write_b32 v226, v219 offset:27056
	ds_write_b32 v226, v220 offset:25536
	ds_write_b32 v226, v221 offset:26064
	ds_write_b32 v226, v222 offset:26592
	ds_write_b32 v226, v223 offset:27120
.Lffn2_wd:
	s_and_b32 s0, s24, 0x3f80
	s_setprio 2
	v_mov_b32_e32 v130, v172
	v_and_b32_e32 v136, 1, v0
	v_lshrrev_b32_e32 v131, 1, v130
	v_and_b32_e32 v131, 0xfffffc0, v131
	v_lshrrev_b32_e32 v132, 3, v130
	v_and_or_b32 v131, v132, 4, v131
	v_and_b32_e32 v130, 0x5f, v130
	v_mul_lo_u32 v131, v131, s5
	v_lshl_add_u32 v130, v130, 2, v131
	v_add_u32_e32 v34, 0x400, v130
	v_add_u32_e32 v34, 0x1000, v130
	v_add_u32_e32 v34, 0x1400, v130
	v_add_u32_e32 v34, 0x2000, v130
	v_add_u32_e32 v34, 0x2400, v130
	v_add_u32_e32 v34, 0x3000, v130
	v_add_u32_e32 v34, 0x3200, v130
	v_add_u32_e32 v34, 0x3400, v130
	v_add_u32_e32 v34, 0x3600, v130
	v_add_u32_e32 v34, 0x4000, v130
	v_add_u32_e32 v2, 0x4400, v130
	v_add_u32_e32 v2, 0x4800, v130
	v_add_u32_e32 v2, 0x5000, v130
	v_add_u32_e32 v2, 0x5400, v130
	v_add_u32_e32 v2, 0x5800, v130
	v_add_u32_e32 v2, 0x6000, v130
	v_add_u32_e32 v2, 0x6400, v130
	v_add_u32_e32 v2, 0x6800, v130
	v_add_u32_e32 v2, 0x7200, v130
	v_add_u32_e32 v2, 0x7400, v130
	v_add_u32_e32 v2, 0x7600, v130
	v_ashrrev_i32_e32 v12, 1, v0
	v_add_u32_e32 v2, 0x7800, v130
	v_add_u32_e32 v130, s0, v12
	v_ashrrev_i32_e32 v131, 31, v130
	v_lshlrev_b64 v[2:3], 11, v[130:131]
	v_lshl_add_u64 v[2:3], s[50:51], 0, v[2:3]
	v_lshl_add_u64 v[2:3], s[36:37], 1, v[2:3]
	v_lshlrev_b32_e32 v4, 7, v136
	v_mov_b32_e32 v5, v1
	v_lshl_add_u64 v[132:133], v[2:3], 0, v[4:5]
	s_waitcnt lgkmcnt(0)
	s_barrier
	global_load_dwordx4 v[6:9], v[132:133], off
	s_add_i32 s0, s0, s35
	v_add_u32_e32 v2, s0, v12
	v_ashrrev_i32_e32 v3, 31, v2
	v_lshlrev_b64 v[2:3], 12, v[2:3]
	v_lshlrev_b32_e32 v0, 8, v136
	v_lshl_add_u64 v[2:3], s[20:21], 0, v[2:3]
	v_mad_u64_u32 v[58:59], s[30:31], v12, s5, v[0:1]
	v_lshl_add_u64 v[10:11], s[36:37], 2, v[2:3]
	ds_read_b128 v[2:5], v58
	v_lshl_add_u64 v[134:135], v[10:11], 0, v[0:1]
	ds_read_b128 v[10:13], v58 offset:16
	s_mov_b64 s[30:31], -1
	s_and_b64 vcc, exec, s[22:23]
	s_waitcnt vmcnt(0)
	v_lshlrev_b32_e32 v14, 16, v6
	v_and_b32_e32 v15, 0xffff0000, v6
	v_lshlrev_b32_e32 v6, 16, v7
	v_and_b32_e32 v7, 0xffff0000, v7
	s_waitcnt lgkmcnt(1)
	v_pk_add_f32 v[4:5], v[4:5], v[6:7]
	v_lshlrev_b32_e32 v6, 16, v8
	v_and_b32_e32 v7, 0xffff0000, v8
	v_lshlrev_b32_e32 v8, 16, v9
	v_and_b32_e32 v9, 0xffff0000, v9
	v_pk_add_f32 v[2:3], v[2:3], v[14:15]
	s_waitcnt lgkmcnt(0)
	v_pk_add_f32 v[6:7], v[10:11], v[6:7]
	v_pk_add_f32 v[8:9], v[12:13], v[8:9]
	s_cbranch_vccz .LBB1_210
	global_store_dwordx4 v[134:135], v[2:5], off
	global_store_dwordx4 v[134:135], v[6:9], off offset:16
	s_mov_b64 s[30:31], 0

; DI int TID() { int t = (int)__builtin_amdgcn_workitem_id_x(); asm volatile("" : "+v"(t)); return t; }
; DI int crow(int r, int hi) { return (r & 3) + 8 * (r >> 2) + 4 * hi; }
; DI void acc_to_cs(const f32x16 (&acc)[2][2], float* Cs) {
;   __builtin_amdgcn_s_setprio(2);
;   const int tid = TID(), lane = tid & 63, w = tid >> 6, wm = w >> 1, wn = w & 1, r32 = lane & 31, hi = lane >> 5;
; #pragma unroll
;   for (int mt = 0; mt < 2; ++mt)
; #pragma unroll
;     for (int nt = 0; nt < 2; ++nt)
; #pragma unroll
;       for (int r = 0; r < 16; ++r) Cs[(wm * 64 + mt * 32 + crow(r, hi)) * CSL + wn * 64 + nt * 32 + r32] = acc[mt][nt][r];
;   __syncthreads();
; }
.Lffn1_epi2:
	v_and_b32_e32 v208, 63, v172
	v_lshrrev_b32_e32 v209, 6, v172
	v_lshrrev_b32_e32 v210, 4, v208
	v_lshlrev_b32_e32 v210, 2, v210
	v_lshrrev_b32_e32 v211, 1, v209
	v_lshl_add_u32 v210, v211, 6, v210
	v_mul_u32_u24_e32 v210, 0x84, v210
	v_and_b32_e32 v211, 1, v209
	v_and_b32_e32 v208, 15, v208
	v_lshl_add_u32 v208, v211, 6, v208
	v_add_lshl_u32 v210, v210, v208, 2
	s_cmp_lg_u32 s0, 0
	s_cbranch_scc1 .Lffn1_w1
	ds_write_b32 v210, v2 offset:0
	ds_write_b32 v210, v3 offset:528
	ds_write_b32 v210, v4 offset:1056
	ds_write_b32 v210, v5 offset:1584
	ds_write_b32 v210, v6 offset:64
	ds_write_b32 v210, v7 offset:592
	ds_write_b32 v210, v8 offset:1120
	ds_write_b32 v210, v9 offset:1648
	ds_write_b32 v210, v10 offset:128
	ds_write_b32 v210, v11 offset:656
	ds_write_b32 v210, v12 offset:1184
	ds_write_b32 v210, v13 offset:1712
	ds_write_b32 v210, v14 offset:192
	ds_write_b32 v210, v15 offset:720
	ds_write_b32 v210, v16 offset:1248
	ds_write_b32 v210, v17 offset:1776
	ds_write_b32 v210, v18 offset:8448
	ds_write_b32 v210, v19 offset:8976
	ds_write_b32 v210, v20 offset:9504
	ds_write_b32 v210, v21 offset:10032
	ds_write_b32 v210, v22 offset:8512
	ds_write_b32 v210, v23 offset:9040
	ds_write_b32 v210, v24 offset:9568
	ds_write_b32 v210, v25 offset:10096
	ds_write_b32 v210, v26 offset:8576
	ds_write_b32 v210, v27 offset:9104
	ds_write_b32 v210, v28 offset:9632
	ds_write_b32 v210, v29 offset:10160
	ds_write_b32 v210, v30 offset:8640
	ds_write_b32 v210, v31 offset:9168
	ds_write_b32 v210, v32 offset:9696
	ds_write_b32 v210, v33 offset:10224
	ds_write_b32 v210, v34 offset:16896
	ds_write_b32 v210, v35 offset:17424
	ds_write_b32 v210, v36 offset:17952
	ds_write_b32 v210, v37 offset:18480
	ds_write_b32 v210, v38 offset:16960
	ds_write_b32 v210, v39 offset:17488
	ds_write_b32 v210, v40 offset:18016
	ds_write_b32 v210, v41 offset:18544
	ds_write_b32 v210, v42 offset:17024
	ds_write_b32 v210, v43 offset:17552
	ds_write_b32 v210, v44 offset:18080
	ds_write_b32 v210, v45 offset:18608
	ds_write_b32 v210, v46 offset:17088
	ds_write_b32 v210, v47 offset:17616
	ds_write_b32 v210, v48 offset:18144
	ds_write_b32 v210, v49 offset:18672
	ds_write_b32 v210, v50 offset:25344
	ds_write_b32 v210, v51 offset:25872
	ds_write_b32 v210, v52 offset:26400
	ds_write_b32 v210, v53 offset:26928
	ds_write_b32 v210, v54 offset:25408
	ds_write_b32 v210, v55 offset:25936
	ds_write_b32 v210, v56 offset:26464
	ds_write_b32 v210, v57 offset:26992
	ds_write_b32 v210, v58 offset:25472
	ds_write_b32 v210, v59 offset:26000
	ds_write_b32 v210, v60 offset:26528
	ds_write_b32 v210, v61 offset:27056
	ds_write_b32 v210, v62 offset:25536
	ds_write_b32 v210, v63 offset:26064
	ds_write_b32 v210, v64 offset:26592
	ds_write_b32 v210, v65 offset:27120
	s_branch .Lffn1_wd
.Lffn1_w1:
	ds_write_b32 v210, v74 offset:0
	ds_write_b32 v210, v75 offset:528
	ds_write_b32 v210, v76 offset:1056
	ds_write_b32 v210, v77 offset:1584
	ds_write_b32 v210, v78 offset:64
	ds_write_b32 v210, v79 offset:592
	ds_write_b32 v210, v80 offset:1120
	ds_write_b32 v210, v81 offset:1648
	ds_write_b32 v210, v82 offset:128
	ds_write_b32 v210, v83 offset:656
	ds_write_b32 v210, v84 offset:1184
	ds_write_b32 v210, v85 offset:1712
	ds_write_b32 v210, v86 offset:192
	ds_write_b32 v210, v87 offset:720
	ds_write_b32 v210, v88 offset:1248
	ds_write_b32 v210, v89 offset:1776
	ds_write_b32 v210, v90 offset:8448
	ds_write_b32 v210, v91 offset:8976
	ds_write_b32 v210, v92 offset:9504
	ds_write_b32 v210, v93 offset:10032
	ds_write_b32 v210, v94 offset:8512
	ds_write_b32 v210, v95 offset:9040
	ds_write_b32 v210, v96 offset:9568
	ds_write_b32 v210, v97 offset:10096
	ds_write_b32 v210, v98 offset:8576
	ds_write_b32 v210, v99 offset:9104
	ds_write_b32 v210, v100 offset:9632
	ds_write_b32 v210, v101 offset:10160
	ds_write_b32 v210, v102 offset:8640
	ds_write_b32 v210, v103 offset:9168
	ds_write_b32 v210, v104 offset:9696
	ds_write_b32 v210, v105 offset:10224
	ds_write_b32 v210, v106 offset:16896
	ds_write_b32 v210, v107 offset:17424
	ds_write_b32 v210, v108 offset:17952
	ds_write_b32 v210, v109 offset:18480
	ds_write_b32 v210, v110 offset:16960
	ds_write_b32 v210, v111 offset:17488
	ds_write_b32 v210, v112 offset:18016
	ds_write_b32 v210, v113 offset:18544
	ds_write_b32 v210, v114 offset:17024
	ds_write_b32 v210, v115 offset:17552
	ds_write_b32 v210, v116 offset:18080
	ds_write_b32 v210, v117 offset:18608
	ds_write_b32 v210, v118 offset:17088
	ds_write_b32 v210, v119 offset:17616
	ds_write_b32 v210, v120 offset:18144
	ds_write_b32 v210, v121 offset:18672
	ds_write_b32 v210, v122 offset:25344
	ds_write_b32 v210, v123 offset:25872
	ds_write_b32 v210, v124 offset:26400
	ds_write_b32 v210, v125 offset:26928
	ds_write_b32 v210, v126 offset:25408
	ds_write_b32 v210, v127 offset:25936
	ds_write_b32 v210, v128 offset:26464
	ds_write_b32 v210, v129 offset:26992
	ds_write_b32 v210, v130 offset:25472
	ds_write_b32 v210, v131 offset:26000
	ds_write_b32 v210, v132 offset:26528
	ds_write_b32 v210, v133 offset:27056
	ds_write_b32 v210, v134 offset:25536
	ds_write_b32 v210, v135 offset:26064
	ds_write_b32 v210, v136 offset:26592
	ds_write_b32 v210, v137 offset:27120
; DI void st8(u16* dst, const float (&v)[8]) { *(u32x4*)dst = pack8(v); }
; DI void tile_ffn1(const Params& p, int l, const Chunk& ck, int tile, int next, PF& pf, char* smem) {
;     ...
;   rowss_finish(rss, rinv_s);
;   acc_to_cs(acc, Cs);
;   const int row = tid >> 1, half = tid & 1; const float rinv = rinv_s[row]; float v[8];
;   u16* dst = (u16*)(p.ws + OFF_H) + (size_t)(m0 + row) * 4096 + n0 + half * 64;
; #pragma unroll
;   for (int c8 = 0; c8 < 8; ++c8) { cs_ld8(Cs, row, half * 64 + c8 * 8, v);
; #pragma unroll
;     for (int j = 0; j < 8; ++j) { const float r = fmaxf(v[j] * rinv, 0.f); v[j] = r * r; }
;     st8(dst + c8 * 8, v); }
.Lffn1_wd:
	s_setprio 2
	v_mov_b32_e32 v0, v172
	s_add_i32 s35, s35, s59
	v_lshrrev_b32_e32 v66, 1, v0
	v_and_b32_e32 v66, 0xfffffc0, v66
	s_waitcnt lgkmcnt(0)
	v_lshrrev_b32_e32 v67, 3, v0
	v_and_or_b32 v66, v67, 4, v66
	v_and_b32_e32 v0, 0x5f, v0
	v_mul_lo_u32 v66, v66, s5
	v_lshl_add_u32 v0, v0, 2, v66
	v_add_u32_e32 v34, 0x400, v0
	v_add_u32_e32 v34, 0x1000, v0
	v_add_u32_e32 v34, 0x1400, v0
	v_add_u32_e32 v34, 0x2000, v0
	v_add_u32_e32 v34, 0x2400, v0
	v_add_u32_e32 v34, 0x3000, v0
	v_add_u32_e32 v34, 0x3200, v0
	v_add_u32_e32 v34, 0x3400, v0
	v_add_u32_e32 v34, 0x3600, v0
	v_add_u32_e32 v34, 0x4000, v0
	v_add_u32_e32 v2, 0x4400, v0
	v_add_u32_e32 v2, 0x4800, v0
	v_add_u32_e32 v2, 0x5000, v0
	v_add_u32_e32 v2, 0x5400, v0
	v_add_u32_e32 v2, 0x5800, v0
	v_add_u32_e32 v2, 0x6000, v0
	v_add_u32_e32 v2, 0x6400, v0
	v_add_u32_e32 v2, 0x6800, v0
	v_add_u32_e32 v2, 0x7200, v0
	v_add_u32_e32 v2, 0x7400, v0
	v_add_u32_e32 v2, 0x7600, v0
	v_add_u32_e32 v0, 0x7800, v0
	v_ashrrev_i32_e32 v4, 1, v148
	v_lshlrev_b32_e32 v0, 6, v148
	v_lshl_add_u32 v5, v4, 2, v201
	v_add_u32_e32 v2, s41, v4
	v_and_b32_e32 v6, 64, v0
	v_mul_lo_u32 v4, v4, s5
	s_waitcnt lgkmcnt(0)
	s_barrier
	v_lshlrev_b32_e32 v0, 15, v6
	v_lshl_add_u32 v20, v6, 2, v4
	ds_read_b32 v21, v5
	ds_read_b128 v[4:7], v20
	v_ashrrev_i32_e32 v3, 31, v2
	v_lshlrev_b64 v[2:3], 6, v[2:3]
	v_lshl_add_u64 v[2:3], s[22:23], 0, v[2:3]
	s_lshl_b64 s[42:43], s[26:27], 15
	v_lshl_add_u64 v[2:3], s[42:43], 0, v[2:3]
	v_lshl_add_u64 v[2:3], v[2:3], 0, v[0:1]
	v_mov_b32_e32 v24, 0x100000
	v_mov_b32_e32 v25, 0
	v_lshl_add_u64 v[22:23], v[2:3], 0, v[24:25]
	s_waitcnt lgkmcnt(0)
	v_mul_f32_e32 v0, v21, v4
	ds_read_b128 v[8:11], v20 offset:16
	ds_read_b128 v[12:15], v20 offset:32
	ds_read_b128 v[16:19], v20 offset:48
	v_max_f32_e32 v4, 0, v0
	v_mul_f32_e32 v0, v21, v5
	v_max_f32_e32 v5, 0, v0
	v_mul_f32_e32 v0, v21, v6
	v_max_f32_e32 v6, 0, v0
	v_mul_f32_e32 v0, v21, v7
	v_max_f32_e32 v7, 0, v0
	s_waitcnt lgkmcnt(2)
	v_mul_f32_e32 v0, v21, v8
	v_max_f32_e32 v8, 0, v0
	v_mul_f32_e32 v0, v21, v9
	v_max_f32_e32 v9, 0, v0
	v_mul_f32_e32 v0, v21, v10
	v_max_f32_e32 v10, 0, v0
	v_mul_f32_e32 v0, v21, v11
	v_max_f32_e32 v11, 0, v0
	v_pk_mul_f32 v[4:5], v[4:5], v[4:5]
	v_pk_mul_f32 v[6:7], v[6:7], v[6:7]
	v_pk_mul_f32 v[8:9], v[8:9], v[8:9]
	v_pk_mul_f32 v[10:11], v[10:11], v[10:11]
	v_cvt_pk_bf16_f32 v4, v4, v5
	v_cvt_pk_bf16_f32 v5, v6, v7
	v_cvt_pk_bf16_f32 v6, v8, v9
	v_cvt_pk_bf16_f32 v7, v10, v11
	s_waitcnt lgkmcnt(1)
	v_mul_f32_e32 v0, v21, v12
	global_store_dwordx4 v[2:3], v[4:7], off
	s_add_i32 s40, s40, s95
	s_and_b64 vcc, exec, s[24:25]
	v_max_f32_e32 v4, 0, v0
	v_mul_f32_e32 v0, v21, v13
	v_max_f32_e32 v5, 0, v0
	v_mul_f32_e32 v0, v21, v14
	v_pk_mul_f32 v[8:9], v[4:5], v[4:5]
	v_max_f32_e32 v4, 0, v0
	v_mul_f32_e32 v0, v21, v15
	v_max_f32_e32 v5, 0, v0
	s_waitcnt lgkmcnt(0)
	v_mul_f32_e32 v0, v21, v16
	v_max_f32_e32 v12, 0, v0
	v_mul_f32_e32 v0, v21, v17
	v_max_f32_e32 v13, 0, v0
	v_mul_f32_e32 v0, v21, v18
	v_pk_mul_f32 v[10:11], v[4:5], v[4:5]
	ds_read_b128 v[4:7], v20 offset:64
	v_max_f32_e32 v14, 0, v0
	v_mul_f32_e32 v0, v21, v19
	v_max_f32_e32 v15, 0, v0
	v_pk_mul_f32 v[12:13], v[12:13], v[12:13]
	v_pk_mul_f32 v[14:15], v[14:15], v[14:15]
	v_cvt_pk_bf16_f32 v8, v8, v9
	v_cvt_pk_bf16_f32 v9, v10, v11
	v_cvt_pk_bf16_f32 v10, v12, v13
	v_cvt_pk_bf16_f32 v11, v14, v15
	global_store_dwordx4 v[2:3], v[8:11], off offset:16
	ds_read_b128 v[8:11], v20 offset:80
	s_waitcnt lgkmcnt(1)
	v_mul_f32_e32 v0, v21, v4
	v_max_f32_e32 v4, 0, v0
	v_mul_f32_e32 v0, v21, v5
	v_max_f32_e32 v5, 0, v0
	v_mul_f32_e32 v0, v21, v6
	v_pk_mul_f32 v[12:13], v[4:5], v[4:5]
	v_max_f32_e32 v4, 0, v0
	v_mul_f32_e32 v0, v21, v7
	v_max_f32_e32 v5, 0, v0
	s_waitcnt lgkmcnt(0)
	v_mul_f32_e32 v0, v21, v8
	v_max_f32_e32 v8, 0, v0
	v_mul_f32_e32 v0, v21, v9
	v_max_f32_e32 v9, 0, v0
	v_mul_f32_e32 v0, v21, v10
	v_pk_mul_f32 v[14:15], v[4:5], v[4:5]
	ds_read_b128 v[4:7], v20 offset:96
	v_pk_mul_f32 v[16:17], v[8:9], v[8:9]
	v_max_f32_e32 v8, 0, v0
	v_mul_f32_e32 v0, v21, v11
	v_max_f32_e32 v9, 0, v0
	v_pk_mul_f32 v[18:19], v[8:9], v[8:9]
	v_cvt_pk_bf16_f32 v8, v12, v13
	v_cvt_pk_bf16_f32 v9, v14, v15
	v_cvt_pk_bf16_f32 v10, v16, v17
	v_cvt_pk_bf16_f32 v11, v18, v19
	global_store_dwordx4 v[2:3], v[8:11], off offset:32
	ds_read_b128 v[8:11], v20 offset:112
	s_waitcnt lgkmcnt(1)
; DI void st8(u16* dst, const float (&v)[8]) { *(u32x4*)dst = pack8(v); }
; DI void tile_ffn1(const Params& p, int l, const Chunk& ck, int tile, int next, PF& pf, char* smem) {
;     ...
;   const int row = tid >> 1, half = tid & 1; const float rinv = rinv_s[row]; float v[8];
;   u16* dst = (u16*)(p.ws + OFF_H) + (size_t)(m0 + row) * 4096 + n0 + half * 64;
; #pragma unroll
;   for (int c8 = 0; c8 < 8; ++c8) { cs_ld8(Cs, row, half * 64 + c8 * 8, v);
; #pragma unroll
;     for (int j = 0; j < 8; ++j) { const float r = fmaxf(v[j] * rinv, 0.f); v[j] = r * r; }
;     st8(dst + c8 * 8, v); }
	v_mul_f32_e32 v0, v21, v4
	v_max_f32_e32 v4, 0, v0
	v_mul_f32_e32 v0, v21, v5
	v_max_f32_e32 v5, 0, v0
	v_mul_f32_e32 v0, v21, v6
	v_pk_mul_f32 v[12:13], v[4:5], v[4:5]
	v_max_f32_e32 v4, 0, v0
	v_mul_f32_e32 v0, v21, v7
	v_max_f32_e32 v5, 0, v0
	s_waitcnt lgkmcnt(0)
	v_mul_f32_e32 v0, v21, v8
	v_max_f32_e32 v8, 0, v0
	v_mul_f32_e32 v0, v21, v9
	v_max_f32_e32 v9, 0, v0
	v_mul_f32_e32 v0, v21, v10
	v_pk_mul_f32 v[14:15], v[4:5], v[4:5]
	ds_read_b128 v[4:7], v20 offset:128
	v_pk_mul_f32 v[16:17], v[8:9], v[8:9]
	v_max_f32_e32 v8, 0, v0
	v_mul_f32_e32 v0, v21, v11
	v_max_f32_e32 v9, 0, v0
	v_pk_mul_f32 v[18:19], v[8:9], v[8:9]
	v_cvt_pk_bf16_f32 v8, v12, v13
	v_cvt_pk_bf16_f32 v9, v14, v15
	v_cvt_pk_bf16_f32 v10, v16, v17
	v_cvt_pk_bf16_f32 v11, v18, v19
	global_store_dwordx4 v[2:3], v[8:11], off offset:48
	ds_read_b128 v[8:11], v20 offset:144
	s_waitcnt lgkmcnt(1)
	v_mul_f32_e32 v0, v21, v4
	v_max_f32_e32 v4, 0, v0
	v_mul_f32_e32 v0, v21, v5
	v_max_f32_e32 v5, 0, v0
	v_mul_f32_e32 v0, v21, v6
	v_pk_mul_f32 v[12:13], v[4:5], v[4:5]
	v_max_f32_e32 v4, 0, v0
	v_mul_f32_e32 v0, v21, v7
	v_max_f32_e32 v5, 0, v0
	s_waitcnt lgkmcnt(0)
	v_mul_f32_e32 v0, v21, v8
	v_max_f32_e32 v8, 0, v0
	v_mul_f32_e32 v0, v21, v9
	v_max_f32_e32 v9, 0, v0
	v_mul_f32_e32 v0, v21, v10
	v_pk_mul_f32 v[14:15], v[4:5], v[4:5]
	ds_read_b128 v[4:7], v20 offset:160
	v_pk_mul_f32 v[16:17], v[8:9], v[8:9]
	v_max_f32_e32 v8, 0, v0
	v_mul_f32_e32 v0, v21, v11
	v_max_f32_e32 v9, 0, v0
	v_pk_mul_f32 v[18:19], v[8:9], v[8:9]
	v_cvt_pk_bf16_f32 v8, v12, v13
	v_cvt_pk_bf16_f32 v9, v14, v15
	v_cvt_pk_bf16_f32 v10, v16, v17
	v_cvt_pk_bf16_f32 v11, v18, v19
	global_store_dwordx4 v[22:23], v[8:11], off
	ds_read_b128 v[8:11], v20 offset:176
	s_waitcnt lgkmcnt(1)
	v_mul_f32_e32 v0, v21, v4
	v_max_f32_e32 v4, 0, v0
	v_mul_f32_e32 v0, v21, v5
	v_max_f32_e32 v5, 0, v0
	v_mul_f32_e32 v0, v21, v6
	v_pk_mul_f32 v[12:13], v[4:5], v[4:5]
	v_max_f32_e32 v4, 0, v0
	v_mul_f32_e32 v0, v21, v7
	v_max_f32_e32 v5, 0, v0
	s_waitcnt lgkmcnt(0)
	v_mul_f32_e32 v0, v21, v8
	v_max_f32_e32 v8, 0, v0
	v_mul_f32_e32 v0, v21, v9
	v_pk_mul_f32 v[14:15], v[4:5], v[4:5]
	ds_read_b128 v[4:7], v20 offset:192
	v_max_f32_e32 v9, 0, v0
	v_mul_f32_e32 v0, v21, v10
	v_pk_mul_f32 v[16:17], v[8:9], v[8:9]
	v_max_f32_e32 v8, 0, v0
	v_mul_f32_e32 v0, v21, v11
	v_max_f32_e32 v9, 0, v0
	v_pk_mul_f32 v[18:19], v[8:9], v[8:9]
	v_cvt_pk_bf16_f32 v8, v12, v13
	v_cvt_pk_bf16_f32 v9, v14, v15
	v_cvt_pk_bf16_f32 v10, v16, v17
	v_cvt_pk_bf16_f32 v11, v18, v19
	global_store_dwordx4 v[22:23], v[8:11], off offset:16
	s_waitcnt lgkmcnt(0)
	v_mul_f32_e32 v0, v21, v4
	ds_read_b128 v[8:11], v20 offset:208
	ds_read_b128 v[12:15], v20 offset:224
	ds_read_b128 v[16:19], v20 offset:240
	v_max_f32_e32 v4, 0, v0
	v_mul_f32_e32 v0, v21, v5
	v_max_f32_e32 v5, 0, v0
	v_mul_f32_e32 v0, v21, v6
	v_max_f32_e32 v6, 0, v0
	v_mul_f32_e32 v0, v21, v7
	v_max_f32_e32 v7, 0, v0
	s_waitcnt lgkmcnt(2)
	v_mul_f32_e32 v0, v21, v8
	v_max_f32_e32 v8, 0, v0
	v_mul_f32_e32 v0, v21, v9
	v_max_f32_e32 v9, 0, v0
	v_mul_f32_e32 v0, v21, v10
	v_max_f32_e32 v10, 0, v0
	v_mul_f32_e32 v0, v21, v11
	v_max_f32_e32 v11, 0, v0
	v_pk_mul_f32 v[4:5], v[4:5], v[4:5]
	v_pk_mul_f32 v[6:7], v[6:7], v[6:7]
	v_pk_mul_f32 v[8:9], v[8:9], v[8:9]
	v_pk_mul_f32 v[10:11], v[10:11], v[10:11]
	v_cvt_pk_bf16_f32 v4, v4, v5
	v_cvt_pk_bf16_f32 v5, v6, v7
	v_cvt_pk_bf16_f32 v6, v8, v9
	v_cvt_pk_bf16_f32 v7, v10, v11
	s_waitcnt lgkmcnt(1)
	v_mul_f32_e32 v0, v21, v12
	global_store_dwordx4 v[22:23], v[4:7], off offset:32
	s_nop 1
	v_max_f32_e32 v4, 0, v0
	v_mul_f32_e32 v0, v21, v13
	v_max_f32_e32 v5, 0, v0
	v_mul_f32_e32 v0, v21, v14
	v_max_f32_e32 v6, 0, v0
	v_mul_f32_e32 v0, v21, v15
	v_max_f32_e32 v7, 0, v0
	s_waitcnt lgkmcnt(0)
	v_mul_f32_e32 v0, v21, v16
	v_max_f32_e32 v8, 0, v0
	v_mul_f32_e32 v0, v21, v17
	v_max_f32_e32 v9, 0, v0
	v_mul_f32_e32 v0, v21, v18
	v_max_f32_e32 v10, 0, v0
	v_mul_f32_e32 v0, v21, v19
	v_max_f32_e32 v11, 0, v0
	v_pk_mul_f32 v[4:5], v[4:5], v[4:5]
	v_pk_mul_f32 v[6:7], v[6:7], v[6:7]
	v_pk_mul_f32 v[8:9], v[8:9], v[8:9]
	v_pk_mul_f32 v[10:11], v[10:11], v[10:11]
	v_cvt_pk_bf16_f32 v4, v4, v5
	v_cvt_pk_bf16_f32 v5, v6, v7
	v_cvt_pk_bf16_f32 v6, v8, v9
	v_cvt_pk_bf16_f32 v7, v10, v11
	global_store_dwordx4 v[22:23], v[4:7], off offset:48
	s_cmp_lg_u32 s0, 0
	s_cbranch_scc1 .Lffn1_p2done
	s_mov_b32 s0, 1
	s_sub_i32 s35, s35, s59
	s_sub_i32 s40, s40, s95
	s_add_u32 s26, s26, 0x80
	s_waitcnt lgkmcnt(0)
	s_barrier
	s_branch .Lffn1_epi2

; DI int TID() { int t = (int)__builtin_amdgcn_workitem_id_x(); asm volatile("" : "+v"(t)); return t; }
; #define BLOAD(A_, B_, kt) do { _Pragma("unroll") for (int i = 0; i < 4; ++i) { \
;     A_[i] = *(const u32x4*)((const char*)Ap + (aoff + (unsigned)(32 * i * lda + (kt) * 64) * 2u)); B_[i] = *(const u32x4*)((const char*)Wt + (woff + (unsigned)(32 * i * K + (kt) * 64) * 2u)); } } while (0)
; DI RowSS rowss_load(const float* ps, int m0) { const int tid = TID(); const float* q = ps + (size_t)(m0 + (tid >> 1)) * 16 + (tid & 1) * 8; RowSS r; r.a = *(const f32x4*)q; r.b = *(const f32x4*)(q + 4); return r; }
; #define BLOAD(A_, B_, kt) do { _Pragma("unroll") for (int i = 0; i < 4; ++i) { \
;     A_[i] = *(const u32x4*)((const char*)Ap + (aoff + (unsigned)(32 * i * lda + (kt) * 64) * 2u)); B_[i] = *(const u32x4*)((const char*)Wt + (woff + (unsigned)(32 * i * K + (kt) * 64) * 2u)); } } while (0)
; template <int NK>
; DI void gemm_run(PF& pf, const u16* __restrict__ Ap, int lda, const u16* __restrict__ Wt, f32x16 (&acc)[2][2], char* smem) {
;   constexpr int K = NK * 64;
;   const int tid = TID(), lane = tid & 63, w = tid >> 6, wm = w >> 1, wn = w & 1, r32 = lane & 31, hi = lane >> 5;
;   u16* As = (u16*)smem; u16* Bs = As + 128 * LDT;
;   const int srow = tid >> 3, sc8 = (tid & 7) * 8;
;   constexpr int nk = NK;
;   const unsigned aoff = (unsigned)(srow * lda + sc8) * 2u, woff = (unsigned)(srow * K + sc8) * 2u;
;     ...
;   __builtin_amdgcn_s_setprio(0);
;   __syncthreads();
;   BSTORE(pf.a0, pf.b0, 0);
;   BLOAD(pf.a0, pf.b0, 2);
;   __syncthreads();
; DI void tile_ffn1(const Params& p, int l, const Chunk& ck, int tile, int next, PF& pf, char* smem) {
;   float* Cs = (float*)smem; float* rinv_s = (float*)(smem + SMEM_CS);
;   const int tid = TID(); const int mi = tile & (MTN - 1), ni = tile >> MTS; const int m0 = mi * 128, n0 = ni * 128;
;   f32x16 acc[2][2]; zero_acc(acc);
;   const RowSS rss = rowss_load((const float*)(p.ws + OFF_PSMID), m0);
;   { const u16* Ap; const u16* Wt; ffn1_ptrs(p, l, tile, Ap, Wt); gemm_run<16>(pf, Ap, 1024, Wt, acc, smem); }
;   if (next >= 0) { const u16* An; const u16* Wn; ffn1_ptrs(p, l, next, An, Wn); gemm_issue(pf, An, 1024, Wn, 1024); }
.LBB1_246:
	s_mov_b32 s26, s16
	s_add_i32 s16, s16, s78
	s_cmpk_gt_i32 s16, 0x7ff
	s_cselect_b64 s[24:25], -1, 0
	s_cmpk_lt_i32 s16, 0x800
	v_mov_b32_e32 v148, v172
	v_mov_b32_e32 v0, v172
	s_cselect_b32 s0, s16, -1
	s_and_b32 s41, s40, 0x3f80
	s_and_b32 s27, s35, 0xfe0000
	v_ashrrev_i32_e32 v2, 1, v0
	v_add_u32_e32 v2, s41, v2
	v_ashrrev_i32_e32 v3, 31, v2
	v_lshlrev_b64 v[2:3], 6, v[2:3]
	v_lshlrev_b32_e32 v0, 5, v0
	v_lshl_add_u64 v[2:3], s[20:21], 0, v[2:3]
	v_and_b32_e32 v0, 32, v0
	v_lshl_add_u64 v[2:3], v[2:3], 0, v[0:1]
	global_load_dwordx4 v[66:69], v[2:3], off offset:16
	global_load_dwordx4 v[70:73], v[2:3], off
	s_and_b32 s26, s26, 0xffffff80
	s_lshl_b32 s26, s26, 1
	s_lshl_b32 s27, s27, 1
	s_add_u32 s28, s17, s27
	s_addc_u32 s29, s34, 0
	s_ashr_i32 s27, s26, 31
	s_lshl_b64 s[30:31], s[26:27], 6
	s_add_u32 s30, s36, s30
	s_addc_u32 s31, s37, s31
	s_setprio 0
	s_waitcnt lgkmcnt(0)
	s_mov_b32 s0, 0
	v_and_b32_e32 v149, 63, v172
	v_lshrrev_b32_e32 v151, 6, v172
	v_bfe_u32 v152, v149, 4, 2
	v_lshrrev_b32_e32 v153, 1, v152
	v_xor_b32_e32 v152, v152, v153
	v_and_b32_e32 v152, 1, v152
	v_lshl_or_b32 v152, v152, 1, v153
	v_xor_b32_e32 v152, v152, v149
	v_and_b32_e32 v152, 3, v152
	v_lshlrev_b32_e32 v152, 4, v152
	v_lshrrev_b32_e32 v153, 2, v149
	v_lshl_add_u32 v142, v151, 5, v153
	v_lshl_add_u32 v142, v142, 11, v152
	v_add_u32_e32 v143, 0x7c00, v142
	v_lshl_add_u32 v144, v151, 6, v153
	v_lshl_add_u32 v144, v144, 6, v152
	v_mov_b32_e32 v145, v144
	v_mov_b32_e32 v146, v144
	v_mov_b32_e32 v147, v144
	v_readfirstlane_b32 s42, v151
	s_lshl_b32 s43, s42, 12
	s_lshl_b32 s42, s42, 11
	s_add_u32 s43, s43, 0x2000
	v_bfe_u32 v152, v149, 2, 2
	v_lshrrev_b32_e32 v153, 1, v152
	v_xor_b32_e32 v152, v152, v153
	v_and_b32_e32 v152, 1, v152
	v_lshl_or_b32 v152, v152, 1, v153
	v_lshrrev_b32_e32 v153, 4, v149
	v_xor_b32_e32 v152, v152, v153
	v_lshlrev_b32_e32 v152, 4, v152
	v_and_b32_e32 v149, 15, v149
	v_lshl_add_u32 v149, v149, 6, v152
	v_lshrrev_b32_e32 v152, 1, v151
	v_and_b32_e32 v153, 1, v151
	v_lshl_add_u32 v138, v152, 12, v149
	v_lshl_add_u32 v140, v153, 12, v149
	v_add_u32_e32 v140, 0x2000, v140
	s_barrier
	v_mov_b32_e32 v2, 0
	v_mov_b32_e32 v3, 0
	v_mov_b32_e32 v4, 0
	v_mov_b32_e32 v5, 0
	v_mov_b32_e32 v6, 0
	v_mov_b32_e32 v7, 0
	v_mov_b32_e32 v8, 0
	v_mov_b32_e32 v9, 0
	v_mov_b32_e32 v10, 0
	v_mov_b32_e32 v11, 0
	v_mov_b32_e32 v12, 0
	v_mov_b32_e32 v13, 0
	v_mov_b32_e32 v14, 0
	v_mov_b32_e32 v15, 0
	v_mov_b32_e32 v16, 0
	v_mov_b32_e32 v17, 0
	v_mov_b32_e32 v18, 0
	v_mov_b32_e32 v19, 0
	v_mov_b32_e32 v20, 0
	v_mov_b32_e32 v21, 0
	v_mov_b32_e32 v22, 0
	v_mov_b32_e32 v23, 0
	v_mov_b32_e32 v24, 0
	v_mov_b32_e32 v25, 0
	v_mov_b32_e32 v26, 0
	v_mov_b32_e32 v27, 0
	v_mov_b32_e32 v28, 0
	v_mov_b32_e32 v29, 0
	v_mov_b32_e32 v30, 0
	v_mov_b32_e32 v31, 0
	v_mov_b32_e32 v32, 0
	v_mov_b32_e32 v33, 0
	v_mov_b32_e32 v34, 0
	v_mov_b32_e32 v35, 0
	v_mov_b32_e32 v36, 0
	v_mov_b32_e32 v37, 0
	v_mov_b32_e32 v38, 0
	v_mov_b32_e32 v39, 0
	v_mov_b32_e32 v40, 0
	v_mov_b32_e32 v41, 0
	v_mov_b32_e32 v42, 0
	v_mov_b32_e32 v43, 0
	v_mov_b32_e32 v44, 0
	v_mov_b32_e32 v45, 0
	v_mov_b32_e32 v46, 0
	v_mov_b32_e32 v47, 0
	v_mov_b32_e32 v48, 0
	v_mov_b32_e32 v49, 0
	v_mov_b32_e32 v50, 0
	v_mov_b32_e32 v51, 0
	v_mov_b32_e32 v52, 0
	v_mov_b32_e32 v53, 0
	v_mov_b32_e32 v54, 0
	v_mov_b32_e32 v55, 0
	v_mov_b32_e32 v56, 0
	v_mov_b32_e32 v57, 0
	v_mov_b32_e32 v58, 0
	v_mov_b32_e32 v59, 0
	v_mov_b32_e32 v60, 0
	v_mov_b32_e32 v61, 0
	v_mov_b32_e32 v62, 0
	v_mov_b32_e32 v63, 0
	v_mov_b32_e32 v64, 0
	v_mov_b32_e32 v65, 0
	v_mov_b32_e32 v74, 0
	v_mov_b32_e32 v75, 0
	v_mov_b32_e32 v76, 0
	v_mov_b32_e32 v77, 0
	v_mov_b32_e32 v78, 0
	v_mov_b32_e32 v79, 0
	v_mov_b32_e32 v80, 0
	v_mov_b32_e32 v81, 0
	v_mov_b32_e32 v82, 0
	v_mov_b32_e32 v83, 0
	v_mov_b32_e32 v84, 0
	v_mov_b32_e32 v85, 0
	v_mov_b32_e32 v86, 0
	v_mov_b32_e32 v87, 0
	v_mov_b32_e32 v88, 0
	v_mov_b32_e32 v89, 0
	v_mov_b32_e32 v90, 0
	v_mov_b32_e32 v91, 0
	v_mov_b32_e32 v92, 0
	v_mov_b32_e32 v93, 0
	v_mov_b32_e32 v94, 0
	v_mov_b32_e32 v95, 0
	v_mov_b32_e32 v96, 0
	v_mov_b32_e32 v97, 0
	v_mov_b32_e32 v98, 0
	v_mov_b32_e32 v99, 0
	v_mov_b32_e32 v100, 0
	v_mov_b32_e32 v101, 0
	v_mov_b32_e32 v102, 0
	v_mov_b32_e32 v103, 0
	v_mov_b32_e32 v104, 0
	v_mov_b32_e32 v105, 0
	v_mov_b32_e32 v106, 0
	v_mov_b32_e32 v107, 0
	v_mov_b32_e32 v108, 0
	v_mov_b32_e32 v109, 0
	v_mov_b32_e32 v110, 0
	v_mov_b32_e32 v111, 0
	v_mov_b32_e32 v112, 0
	v_mov_b32_e32 v113, 0
	v_mov_b32_e32 v114, 0
	v_mov_b32_e32 v115, 0
	v_mov_b32_e32 v116, 0
	v_mov_b32_e32 v117, 0
	v_mov_b32_e32 v118, 0
	v_mov_b32_e32 v119, 0
	v_mov_b32_e32 v120, 0
	v_mov_b32_e32 v121, 0
	v_mov_b32_e32 v122, 0
	v_mov_b32_e32 v123, 0
	v_mov_b32_e32 v124, 0
	v_mov_b32_e32 v125, 0
	v_mov_b32_e32 v126, 0
	v_mov_b32_e32 v127, 0
	v_mov_b32_e32 v128, 0
	v_mov_b32_e32 v129, 0
	v_mov_b32_e32 v130, 0
	v_mov_b32_e32 v131, 0
	v_mov_b32_e32 v132, 0
	v_mov_b32_e32 v133, 0
	v_mov_b32_e32 v134, 0
	v_mov_b32_e32 v135, 0
	v_mov_b32_e32 v136, 0
	v_mov_b32_e32 v137, 0
	s_add_u32 m0, s42, 0x0
	s_nop 0
	global_load_lds_dwordx4 v142, s[28:29]
	global_load_lds_dwordx4 v143, s[28:29] offset:1024
	s_add_u32 m0, s43, 0x0
	s_nop 0
	global_load_lds_dwordx4 v144, s[30:31]
	global_load_lds_dwordx4 v145, s[30:31] offset:1024
	global_load_lds_dwordx4 v146, s[30:31] offset:2048
	global_load_lds_dwordx4 v147, s[30:31] offset:3072
	s_add_u32 m0, s42, 0x6000
	s_add_u32 s28, s28, 0x40
	s_addc_u32 s29, s29, 0
	global_load_lds_dwordx4 v142, s[28:29]
	global_load_lds_dwordx4 v143, s[28:29] offset:1024
	s_add_u32 m0, s43, 0x6000
	s_add_u32 s30, s30, 0x40000
	s_addc_u32 s31, s31, 0
	global_load_lds_dwordx4 v144, s[30:31]
	global_load_lds_dwordx4 v145, s[30:31] offset:1024
	global_load_lds_dwordx4 v146, s[30:31] offset:2048
	global_load_lds_dwordx4 v147, s[30:31] offset:3072
	s_mov_b32 s46, 10
; #define BLOAD(A_, B_, kt) do { _Pragma("unroll") for (int i = 0; i < 4; ++i) { \
;     A_[i] = *(const u32x4*)((const char*)Ap + (aoff + (unsigned)(32 * i * lda + (kt) * 64) * 2u)); B_[i] = *(const u32x4*)((const char*)Wt + (woff + (unsigned)(32 * i * K + (kt) * 64) * 2u)); } } while (0)
; #define BLOAD(A_, B_, kt) do { _Pragma("unroll") for (int i = 0; i < 4; ++i) { \
;     A_[i] = *(const u32x4*)((const char*)Ap + (aoff + (unsigned)(32 * i * lda + (kt) * 64) * 2u)); B_[i] = *(const u32x4*)((const char*)Wt + (woff + (unsigned)(32 * i * K + (kt) * 64) * 2u)); } } while (0)
; #define BSTORE(A_, B_, buf) do { _Pragma("unroll") for (int i = 0; i < 4; ++i) { \
;     *(u32x4*)&As[(buf) * GBUF + (srow + 32 * i) * LDT + sc8] = A_[i]; \
;     *(u32x4*)&Bs[(buf) * GBUF + (srow + 32 * i) * LDT + sc8] = B_[i]; } } while (0)
; template <int NK>
; DI void gemm_run(PF& pf, const u16* __restrict__ Ap, int lda, const u16* __restrict__ Wt, f32x16 (&acc)[2][2], char* smem) {
;     ...
;   __builtin_amdgcn_s_setprio(0);
;   __syncthreads();
;   BSTORE(pf.a0, pf.b0, 0);
;   BLOAD(pf.a0, pf.b0, 2);
;   __syncthreads();
; #pragma unroll
;   for (int kt = 0; kt < nk; kt += 2) {
;     BCOMP(0);
;     BSTORE(pf.a1, pf.b1, 1);
;     if (kt + 3 < nk) BLOAD(pf.a1, pf.b1, kt + 3);
;     __syncthreads();
;     BCOMP(1);
;     if (kt + 2 < nk) { BSTORE(pf.a0, pf.b0, 0); if (kt + 4 < nk) BLOAD(pf.a0, pf.b0, kt + 4); }
;     __syncthreads();
.Lffn1_kloop:
	s_waitcnt vmcnt(6)
	s_barrier
	s_setprio 1
	ds_read_b128 v[208:211], v138 offset:0
	ds_read_b128 v[224:227], v140 offset:0
	ds_read_b128 v[228:231], v140 offset:1024
	ds_read_b128 v[232:235], v140 offset:2048
	ds_read_b128 v[236:239], v140 offset:3072
	ds_read_b128 v[212:215], v138 offset:1024
	ds_read_b128 v[216:219], v138 offset:2048
	ds_read_b128 v[220:223], v138 offset:3072
	ds_read_b128 v[240:243], v140 offset:8192
	ds_read_b128 v[244:247], v140 offset:9216
	ds_read_b128 v[248:251], v140 offset:10240
	ds_read_b128 v[156:159], v140 offset:11264
	s_add_u32 m0, s42, 0xc000
	s_add_u32 s28, s28, 0x40
	s_addc_u32 s29, s29, 0
	global_load_lds_dwordx4 v142, s[28:29]
	global_load_lds_dwordx4 v143, s[28:29] offset:1024
	s_add_u32 m0, s43, 0xc000
	s_add_u32 s30, s30, 0x40000
	s_addc_u32 s31, s31, 0
	global_load_lds_dwordx4 v144, s[30:31]
	global_load_lds_dwordx4 v145, s[30:31] offset:1024
	global_load_lds_dwordx4 v146, s[30:31] offset:2048
	global_load_lds_dwordx4 v147, s[30:31] offset:3072
	s_waitcnt lgkmcnt(10)
	v_mfma_f32_16x16x32_bf16 v[2:5], v[208:211], v[224:227], v[2:5]
	s_waitcnt lgkmcnt(9)
	v_mfma_f32_16x16x32_bf16 v[6:9], v[208:211], v[228:231], v[6:9]
	s_waitcnt lgkmcnt(8)
	v_mfma_f32_16x16x32_bf16 v[10:13], v[208:211], v[232:235], v[10:13]
	s_waitcnt lgkmcnt(7)
	v_mfma_f32_16x16x32_bf16 v[14:17], v[208:211], v[236:239], v[14:17]
	s_waitcnt lgkmcnt(6)
	v_mfma_f32_16x16x32_bf16 v[18:21], v[212:215], v[224:227], v[18:21]
	v_mfma_f32_16x16x32_bf16 v[22:25], v[212:215], v[228:231], v[22:25]
	v_mfma_f32_16x16x32_bf16 v[26:29], v[212:215], v[232:235], v[26:29]
	v_mfma_f32_16x16x32_bf16 v[30:33], v[212:215], v[236:239], v[30:33]
	s_waitcnt lgkmcnt(5)
	v_mfma_f32_16x16x32_bf16 v[34:37], v[216:219], v[224:227], v[34:37]
	v_mfma_f32_16x16x32_bf16 v[38:41], v[216:219], v[228:231], v[38:41]
	v_mfma_f32_16x16x32_bf16 v[42:45], v[216:219], v[232:235], v[42:45]
	v_mfma_f32_16x16x32_bf16 v[46:49], v[216:219], v[236:239], v[46:49]
	s_waitcnt lgkmcnt(4)
	v_mfma_f32_16x16x32_bf16 v[50:53], v[220:223], v[224:227], v[50:53]
	v_mfma_f32_16x16x32_bf16 v[54:57], v[220:223], v[228:231], v[54:57]
	v_mfma_f32_16x16x32_bf16 v[58:61], v[220:223], v[232:235], v[58:61]
	v_mfma_f32_16x16x32_bf16 v[62:65], v[220:223], v[236:239], v[62:65]
	s_waitcnt lgkmcnt(3)
	v_mfma_f32_16x16x32_bf16 v[74:77], v[208:211], v[240:243], v[74:77]
	s_waitcnt lgkmcnt(2)
	v_mfma_f32_16x16x32_bf16 v[78:81], v[208:211], v[244:247], v[78:81]
	s_waitcnt lgkmcnt(1)
	v_mfma_f32_16x16x32_bf16 v[82:85], v[208:211], v[248:251], v[82:85]
	s_waitcnt lgkmcnt(0)
	v_mfma_f32_16x16x32_bf16 v[86:89], v[208:211], v[156:159], v[86:89]
	v_mfma_f32_16x16x32_bf16 v[90:93], v[212:215], v[240:243], v[90:93]
	v_mfma_f32_16x16x32_bf16 v[94:97], v[212:215], v[244:247], v[94:97]
	v_mfma_f32_16x16x32_bf16 v[98:101], v[212:215], v[248:251], v[98:101]
	v_mfma_f32_16x16x32_bf16 v[102:105], v[212:215], v[156:159], v[102:105]
	v_mfma_f32_16x16x32_bf16 v[106:109], v[216:219], v[240:243], v[106:109]
	v_mfma_f32_16x16x32_bf16 v[110:113], v[216:219], v[244:247], v[110:113]
	v_mfma_f32_16x16x32_bf16 v[114:117], v[216:219], v[248:251], v[114:117]
	v_mfma_f32_16x16x32_bf16 v[118:121], v[216:219], v[156:159], v[118:121]
	v_mfma_f32_16x16x32_bf16 v[122:125], v[220:223], v[240:243], v[122:125]
	v_mfma_f32_16x16x32_bf16 v[126:129], v[220:223], v[244:247], v[126:129]
	v_mfma_f32_16x16x32_bf16 v[130:133], v[220:223], v[248:251], v[130:133]
	v_mfma_f32_16x16x32_bf16 v[134:137], v[220:223], v[156:159], v[134:137]
	s_setprio 0
	s_waitcnt vmcnt(6)
	s_barrier
	s_setprio 1
	ds_read_b128 v[208:211], v138 offset:24576
	ds_read_b128 v[224:227], v140 offset:24576
	ds_read_b128 v[228:231], v140 offset:25600
	ds_read_b128 v[232:235], v140 offset:26624
	ds_read_b128 v[236:239], v140 offset:27648
	ds_read_b128 v[212:215], v138 offset:25600
	ds_read_b128 v[216:219], v138 offset:26624
	ds_read_b128 v[220:223], v138 offset:27648
	ds_read_b128 v[240:243], v140 offset:32768
	ds_read_b128 v[244:247], v140 offset:33792
	ds_read_b128 v[248:251], v140 offset:34816
	ds_read_b128 v[156:159], v140 offset:35840
	s_add_u32 m0, s42, 0x0
	s_add_u32 s28, s28, 0x40
	s_addc_u32 s29, s29, 0
	global_load_lds_dwordx4 v142, s[28:29]
	global_load_lds_dwordx4 v143, s[28:29] offset:1024
	s_add_u32 m0, s43, 0x0
	s_add_u32 s30, s30, 0x40000
	s_addc_u32 s31, s31, 0
	global_load_lds_dwordx4 v144, s[30:31]
	global_load_lds_dwordx4 v145, s[30:31] offset:1024
	global_load_lds_dwordx4 v146, s[30:31] offset:2048
	global_load_lds_dwordx4 v147, s[30:31] offset:3072
	s_waitcnt lgkmcnt(10)
	v_mfma_f32_16x16x32_bf16 v[2:5], v[208:211], v[224:227], v[2:5]
	s_waitcnt lgkmcnt(9)
	v_mfma_f32_16x16x32_bf16 v[6:9], v[208:211], v[228:231], v[6:9]
	s_waitcnt lgkmcnt(8)
	v_mfma_f32_16x16x32_bf16 v[10:13], v[208:211], v[232:235], v[10:13]
	s_waitcnt lgkmcnt(7)
	v_mfma_f32_16x16x32_bf16 v[14:17], v[208:211], v[236:239], v[14:17]
	s_waitcnt lgkmcnt(6)
	v_mfma_f32_16x16x32_bf16 v[18:21], v[212:215], v[224:227], v[18:21]
	v_mfma_f32_16x16x32_bf16 v[22:25], v[212:215], v[228:231], v[22:25]
	v_mfma_f32_16x16x32_bf16 v[26:29], v[212:215], v[232:235], v[26:29]
	v_mfma_f32_16x16x32_bf16 v[30:33], v[212:215], v[236:239], v[30:33]
	s_waitcnt lgkmcnt(5)
	v_mfma_f32_16x16x32_bf16 v[34:37], v[216:219], v[224:227], v[34:37]
	v_mfma_f32_16x16x32_bf16 v[38:41], v[216:219], v[228:231], v[38:41]
	v_mfma_f32_16x16x32_bf16 v[42:45], v[216:219], v[232:235], v[42:45]
	v_mfma_f32_16x16x32_bf16 v[46:49], v[216:219], v[236:239], v[46:49]
	s_waitcnt lgkmcnt(4)
	v_mfma_f32_16x16x32_bf16 v[50:53], v[220:223], v[224:227], v[50:53]
	v_mfma_f32_16x16x32_bf16 v[54:57], v[220:223], v[228:231], v[54:57]
	v_mfma_f32_16x16x32_bf16 v[58:61], v[220:223], v[232:235], v[58:61]
	v_mfma_f32_16x16x32_bf16 v[62:65], v[220:223], v[236:239], v[62:65]
	s_waitcnt lgkmcnt(3)
	v_mfma_f32_16x16x32_bf16 v[74:77], v[208:211], v[240:243], v[74:77]
	s_waitcnt lgkmcnt(2)
	v_mfma_f32_16x16x32_bf16 v[78:81], v[208:211], v[244:247], v[78:81]
	s_waitcnt lgkmcnt(1)
	v_mfma_f32_16x16x32_bf16 v[82:85], v[208:211], v[248:251], v[82:85]
	s_waitcnt lgkmcnt(0)
	v_mfma_f32_16x16x32_bf16 v[86:89], v[208:211], v[156:159], v[86:89]
	v_mfma_f32_16x16x32_bf16 v[90:93], v[212:215], v[240:243], v[90:93]
	v_mfma_f32_16x16x32_bf16 v[94:97], v[212:215], v[244:247], v[94:97]
	v_mfma_f32_16x16x32_bf16 v[98:101], v[212:215], v[248:251], v[98:101]
	v_mfma_f32_16x16x32_bf16 v[102:105], v[212:215], v[156:159], v[102:105]
	v_mfma_f32_16x16x32_bf16 v[106:109], v[216:219], v[240:243], v[106:109]
	v_mfma_f32_16x16x32_bf16 v[110:113], v[216:219], v[244:247], v[110:113]
	v_mfma_f32_16x16x32_bf16 v[114:117], v[216:219], v[248:251], v[114:117]
	v_mfma_f32_16x16x32_bf16 v[118:121], v[216:219], v[156:159], v[118:121]
	v_mfma_f32_16x16x32_bf16 v[122:125], v[220:223], v[240:243], v[122:125]
	v_mfma_f32_16x16x32_bf16 v[126:129], v[220:223], v[244:247], v[126:129]
	v_mfma_f32_16x16x32_bf16 v[130:133], v[220:223], v[248:251], v[130:133]
	v_mfma_f32_16x16x32_bf16 v[134:137], v[220:223], v[156:159], v[134:137]
	s_setprio 0
	s_waitcnt vmcnt(6)
	s_barrier
; #define BLOAD(A_, B_, kt) do { _Pragma("unroll") for (int i = 0; i < 4; ++i) { \
;     A_[i] = *(const u32x4*)((const char*)Ap + (aoff + (unsigned)(32 * i * lda + (kt) * 64) * 2u)); B_[i] = *(const u32x4*)((const char*)Wt + (woff + (unsigned)(32 * i * K + (kt) * 64) * 2u)); } } while (0)
; #define BLOAD(A_, B_, kt) do { _Pragma("unroll") for (int i = 0; i < 4; ++i) { \
;     A_[i] = *(const u32x4*)((const char*)Ap + (aoff + (unsigned)(32 * i * lda + (kt) * 64) * 2u)); B_[i] = *(const u32x4*)((const char*)Wt + (woff + (unsigned)(32 * i * K + (kt) * 64) * 2u)); } } while (0)
; #define BSTORE(A_, B_, buf) do { _Pragma("unroll") for (int i = 0; i < 4; ++i) { \
;     *(u32x4*)&As[(buf) * GBUF + (srow + 32 * i) * LDT + sc8] = A_[i]; \
;     *(u32x4*)&Bs[(buf) * GBUF + (srow + 32 * i) * LDT + sc8] = B_[i]; } } while (0)
; template <int NK>
; DI void gemm_run(PF& pf, const u16* __restrict__ Ap, int lda, const u16* __restrict__ Wt, f32x16 (&acc)[2][2], char* smem) {
;     ...
;   __builtin_amdgcn_s_setprio(0);
;   __syncthreads();
;   BSTORE(pf.a0, pf.b0, 0);
;   BLOAD(pf.a0, pf.b0, 2);
;   __syncthreads();
; #pragma unroll
;   for (int kt = 0; kt < nk; kt += 2) {
;     BCOMP(0);
;     BSTORE(pf.a1, pf.b1, 1);
;     if (kt + 3 < nk) BLOAD(pf.a1, pf.b1, kt + 3);
;     __syncthreads();
;     BCOMP(1);
;     if (kt + 2 < nk) { BSTORE(pf.a0, pf.b0, 0); if (kt + 4 < nk) BLOAD(pf.a0, pf.b0, kt + 4); }
;     __syncthreads();
	s_setprio 1
	ds_read_b128 v[208:211], v138 offset:49152
	ds_read_b128 v[224:227], v140 offset:49152
	ds_read_b128 v[228:231], v140 offset:50176
	ds_read_b128 v[232:235], v140 offset:51200
	ds_read_b128 v[236:239], v140 offset:52224
	ds_read_b128 v[212:215], v138 offset:50176
	ds_read_b128 v[216:219], v138 offset:51200
	ds_read_b128 v[220:223], v138 offset:52224
	ds_read_b128 v[240:243], v140 offset:57344
	ds_read_b128 v[244:247], v140 offset:58368
	ds_read_b128 v[248:251], v140 offset:59392
	ds_read_b128 v[156:159], v140 offset:60416
	s_add_u32 m0, s42, 0x6000
	s_add_u32 s28, s28, 0x40
	s_addc_u32 s29, s29, 0
	global_load_lds_dwordx4 v142, s[28:29]
	global_load_lds_dwordx4 v143, s[28:29] offset:1024
	s_add_u32 m0, s43, 0x6000
	s_add_u32 s30, s30, 0x40000
	s_addc_u32 s31, s31, 0
	global_load_lds_dwordx4 v144, s[30:31]
	global_load_lds_dwordx4 v145, s[30:31] offset:1024
	global_load_lds_dwordx4 v146, s[30:31] offset:2048
	global_load_lds_dwordx4 v147, s[30:31] offset:3072
	s_waitcnt lgkmcnt(10)
	v_mfma_f32_16x16x32_bf16 v[2:5], v[208:211], v[224:227], v[2:5]
	s_waitcnt lgkmcnt(9)
	v_mfma_f32_16x16x32_bf16 v[6:9], v[208:211], v[228:231], v[6:9]
	s_waitcnt lgkmcnt(8)
	v_mfma_f32_16x16x32_bf16 v[10:13], v[208:211], v[232:235], v[10:13]
	s_waitcnt lgkmcnt(7)
	v_mfma_f32_16x16x32_bf16 v[14:17], v[208:211], v[236:239], v[14:17]
	s_waitcnt lgkmcnt(6)
	v_mfma_f32_16x16x32_bf16 v[18:21], v[212:215], v[224:227], v[18:21]
	v_mfma_f32_16x16x32_bf16 v[22:25], v[212:215], v[228:231], v[22:25]
	v_mfma_f32_16x16x32_bf16 v[26:29], v[212:215], v[232:235], v[26:29]
	v_mfma_f32_16x16x32_bf16 v[30:33], v[212:215], v[236:239], v[30:33]
	s_waitcnt lgkmcnt(5)
	v_mfma_f32_16x16x32_bf16 v[34:37], v[216:219], v[224:227], v[34:37]
	v_mfma_f32_16x16x32_bf16 v[38:41], v[216:219], v[228:231], v[38:41]
	v_mfma_f32_16x16x32_bf16 v[42:45], v[216:219], v[232:235], v[42:45]
	v_mfma_f32_16x16x32_bf16 v[46:49], v[216:219], v[236:239], v[46:49]
	s_waitcnt lgkmcnt(4)
	v_mfma_f32_16x16x32_bf16 v[50:53], v[220:223], v[224:227], v[50:53]
	v_mfma_f32_16x16x32_bf16 v[54:57], v[220:223], v[228:231], v[54:57]
	v_mfma_f32_16x16x32_bf16 v[58:61], v[220:223], v[232:235], v[58:61]
	v_mfma_f32_16x16x32_bf16 v[62:65], v[220:223], v[236:239], v[62:65]
	s_waitcnt lgkmcnt(3)
	v_mfma_f32_16x16x32_bf16 v[74:77], v[208:211], v[240:243], v[74:77]
	s_waitcnt lgkmcnt(2)
	v_mfma_f32_16x16x32_bf16 v[78:81], v[208:211], v[244:247], v[78:81]
	s_waitcnt lgkmcnt(1)
	v_mfma_f32_16x16x32_bf16 v[82:85], v[208:211], v[248:251], v[82:85]
	s_waitcnt lgkmcnt(0)
	v_mfma_f32_16x16x32_bf16 v[86:89], v[208:211], v[156:159], v[86:89]
	v_mfma_f32_16x16x32_bf16 v[90:93], v[212:215], v[240:243], v[90:93]
	v_mfma_f32_16x16x32_bf16 v[94:97], v[212:215], v[244:247], v[94:97]
	v_mfma_f32_16x16x32_bf16 v[98:101], v[212:215], v[248:251], v[98:101]
	v_mfma_f32_16x16x32_bf16 v[102:105], v[212:215], v[156:159], v[102:105]
	v_mfma_f32_16x16x32_bf16 v[106:109], v[216:219], v[240:243], v[106:109]
	v_mfma_f32_16x16x32_bf16 v[110:113], v[216:219], v[244:247], v[110:113]
	v_mfma_f32_16x16x32_bf16 v[114:117], v[216:219], v[248:251], v[114:117]
	v_mfma_f32_16x16x32_bf16 v[118:121], v[216:219], v[156:159], v[118:121]
	v_mfma_f32_16x16x32_bf16 v[122:125], v[220:223], v[240:243], v[122:125]
	v_mfma_f32_16x16x32_bf16 v[126:129], v[220:223], v[244:247], v[126:129]
	v_mfma_f32_16x16x32_bf16 v[130:133], v[220:223], v[248:251], v[130:133]
	v_mfma_f32_16x16x32_bf16 v[134:137], v[220:223], v[156:159], v[134:137]
	s_setprio 0
	s_sub_u32 s46, s46, 1
	s_cmp_lg_u32 s46, 0
	s_cbranch_scc1 .Lffn1_kloop
	s_waitcnt vmcnt(6)
	s_barrier
; #define BLOAD(A_, B_, kt) do { _Pragma("unroll") for (int i = 0; i < 4; ++i) { \
;     A_[i] = *(const u32x4*)((const char*)Ap + (aoff + (unsigned)(32 * i * lda + (kt) * 64) * 2u)); B_[i] = *(const u32x4*)((const char*)Wt + (woff + (unsigned)(32 * i * K + (kt) * 64) * 2u)); } } while (0)
; #define BLOAD(A_, B_, kt) do { _Pragma("unroll") for (int i = 0; i < 4; ++i) { \
;     A_[i] = *(const u32x4*)((const char*)Ap + (aoff + (unsigned)(32 * i * lda + (kt) * 64) * 2u)); B_[i] = *(const u32x4*)((const char*)Wt + (woff + (unsigned)(32 * i * K + (kt) * 64) * 2u)); } } while (0)
; #define BSTORE(A_, B_, buf) do { _Pragma("unroll") for (int i = 0; i < 4; ++i) { \
;     *(u32x4*)&As[(buf) * GBUF + (srow + 32 * i) * LDT + sc8] = A_[i]; \
;     *(u32x4*)&Bs[(buf) * GBUF + (srow + 32 * i) * LDT + sc8] = B_[i]; } } while (0)
; template <int NK>
; DI void gemm_run(PF& pf, const u16* __restrict__ Ap, int lda, const u16* __restrict__ Wt, f32x16 (&acc)[2][2], char* smem) {
;     ...
; #pragma unroll
;   for (int kt = 0; kt < nk; kt += 2) {
;     BCOMP(0);
;     BSTORE(pf.a1, pf.b1, 1);
;     if (kt + 3 < nk) BLOAD(pf.a1, pf.b1, kt + 3);
;     __syncthreads();
;     BCOMP(1);
;     if (kt + 2 < nk) { BSTORE(pf.a0, pf.b0, 0); if (kt + 4 < nk) BLOAD(pf.a0, pf.b0, kt + 4); }
;     __syncthreads();
;   }
	s_setprio 1
	ds_read_b128 v[208:211], v138 offset:0
	ds_read_b128 v[224:227], v140 offset:0
	ds_read_b128 v[228:231], v140 offset:1024
	ds_read_b128 v[232:235], v140 offset:2048
	ds_read_b128 v[236:239], v140 offset:3072
	ds_read_b128 v[212:215], v138 offset:1024
	ds_read_b128 v[216:219], v138 offset:2048
	ds_read_b128 v[220:223], v138 offset:3072
	ds_read_b128 v[240:243], v140 offset:8192
	ds_read_b128 v[244:247], v140 offset:9216
	ds_read_b128 v[248:251], v140 offset:10240
	ds_read_b128 v[156:159], v140 offset:11264
	s_waitcnt lgkmcnt(10)
	v_mfma_f32_16x16x32_bf16 v[2:5], v[208:211], v[224:227], v[2:5]
	s_waitcnt lgkmcnt(9)
	v_mfma_f32_16x16x32_bf16 v[6:9], v[208:211], v[228:231], v[6:9]
	s_waitcnt lgkmcnt(8)
	v_mfma_f32_16x16x32_bf16 v[10:13], v[208:211], v[232:235], v[10:13]
	s_waitcnt lgkmcnt(7)
	v_mfma_f32_16x16x32_bf16 v[14:17], v[208:211], v[236:239], v[14:17]
	s_waitcnt lgkmcnt(6)
	v_mfma_f32_16x16x32_bf16 v[18:21], v[212:215], v[224:227], v[18:21]
	v_mfma_f32_16x16x32_bf16 v[22:25], v[212:215], v[228:231], v[22:25]
	v_mfma_f32_16x16x32_bf16 v[26:29], v[212:215], v[232:235], v[26:29]
	v_mfma_f32_16x16x32_bf16 v[30:33], v[212:215], v[236:239], v[30:33]
	s_waitcnt lgkmcnt(5)
	v_mfma_f32_16x16x32_bf16 v[34:37], v[216:219], v[224:227], v[34:37]
	v_mfma_f32_16x16x32_bf16 v[38:41], v[216:219], v[228:231], v[38:41]
	v_mfma_f32_16x16x32_bf16 v[42:45], v[216:219], v[232:235], v[42:45]
	v_mfma_f32_16x16x32_bf16 v[46:49], v[216:219], v[236:239], v[46:49]
	s_waitcnt lgkmcnt(4)
	v_mfma_f32_16x16x32_bf16 v[50:53], v[220:223], v[224:227], v[50:53]
	v_mfma_f32_16x16x32_bf16 v[54:57], v[220:223], v[228:231], v[54:57]
	v_mfma_f32_16x16x32_bf16 v[58:61], v[220:223], v[232:235], v[58:61]
	v_mfma_f32_16x16x32_bf16 v[62:65], v[220:223], v[236:239], v[62:65]
	s_waitcnt lgkmcnt(3)
	v_mfma_f32_16x16x32_bf16 v[74:77], v[208:211], v[240:243], v[74:77]
	s_waitcnt lgkmcnt(2)
	v_mfma_f32_16x16x32_bf16 v[78:81], v[208:211], v[244:247], v[78:81]
	s_waitcnt lgkmcnt(1)
	v_mfma_f32_16x16x32_bf16 v[82:85], v[208:211], v[248:251], v[82:85]
	s_waitcnt lgkmcnt(0)
	v_mfma_f32_16x16x32_bf16 v[86:89], v[208:211], v[156:159], v[86:89]
	v_mfma_f32_16x16x32_bf16 v[90:93], v[212:215], v[240:243], v[90:93]
	v_mfma_f32_16x16x32_bf16 v[94:97], v[212:215], v[244:247], v[94:97]
	v_mfma_f32_16x16x32_bf16 v[98:101], v[212:215], v[248:251], v[98:101]
	v_mfma_f32_16x16x32_bf16 v[102:105], v[212:215], v[156:159], v[102:105]
	v_mfma_f32_16x16x32_bf16 v[106:109], v[216:219], v[240:243], v[106:109]
	v_mfma_f32_16x16x32_bf16 v[110:113], v[216:219], v[244:247], v[110:113]
	v_mfma_f32_16x16x32_bf16 v[114:117], v[216:219], v[248:251], v[114:117]
	v_mfma_f32_16x16x32_bf16 v[118:121], v[216:219], v[156:159], v[118:121]
	v_mfma_f32_16x16x32_bf16 v[122:125], v[220:223], v[240:243], v[122:125]
	v_mfma_f32_16x16x32_bf16 v[126:129], v[220:223], v[244:247], v[126:129]
	v_mfma_f32_16x16x32_bf16 v[130:133], v[220:223], v[248:251], v[130:133]
	v_mfma_f32_16x16x32_bf16 v[134:137], v[220:223], v[156:159], v[134:137]
	s_setprio 0
	s_waitcnt vmcnt(0)
	s_barrier
	s_setprio 1
	ds_read_b128 v[208:211], v138 offset:24576
	ds_read_b128 v[224:227], v140 offset:24576
	ds_read_b128 v[228:231], v140 offset:25600
	ds_read_b128 v[232:235], v140 offset:26624
	ds_read_b128 v[236:239], v140 offset:27648
	ds_read_b128 v[212:215], v138 offset:25600
	ds_read_b128 v[216:219], v138 offset:26624
	ds_read_b128 v[220:223], v138 offset:27648
	ds_read_b128 v[240:243], v140 offset:32768
	ds_read_b128 v[244:247], v140 offset:33792
	ds_read_b128 v[248:251], v140 offset:34816
	ds_read_b128 v[156:159], v140 offset:35840
	s_waitcnt lgkmcnt(10)
	v_mfma_f32_16x16x32_bf16 v[2:5], v[208:211], v[224:227], v[2:5]
	s_waitcnt lgkmcnt(9)
	v_mfma_f32_16x16x32_bf16 v[6:9], v[208:211], v[228:231], v[6:9]
	s_waitcnt lgkmcnt(8)
	v_mfma_f32_16x16x32_bf16 v[10:13], v[208:211], v[232:235], v[10:13]
	s_waitcnt lgkmcnt(7)
	v_mfma_f32_16x16x32_bf16 v[14:17], v[208:211], v[236:239], v[14:17]
	s_waitcnt lgkmcnt(6)
	v_mfma_f32_16x16x32_bf16 v[18:21], v[212:215], v[224:227], v[18:21]
	v_mfma_f32_16x16x32_bf16 v[22:25], v[212:215], v[228:231], v[22:25]
	v_mfma_f32_16x16x32_bf16 v[26:29], v[212:215], v[232:235], v[26:29]
	v_mfma_f32_16x16x32_bf16 v[30:33], v[212:215], v[236:239], v[30:33]
	s_waitcnt lgkmcnt(5)
	v_mfma_f32_16x16x32_bf16 v[34:37], v[216:219], v[224:227], v[34:37]
	v_mfma_f32_16x16x32_bf16 v[38:41], v[216:219], v[228:231], v[38:41]
	v_mfma_f32_16x16x32_bf16 v[42:45], v[216:219], v[232:235], v[42:45]
	v_mfma_f32_16x16x32_bf16 v[46:49], v[216:219], v[236:239], v[46:49]
	s_waitcnt lgkmcnt(4)
	v_mfma_f32_16x16x32_bf16 v[50:53], v[220:223], v[224:227], v[50:53]
	v_mfma_f32_16x16x32_bf16 v[54:57], v[220:223], v[228:231], v[54:57]
	v_mfma_f32_16x16x32_bf16 v[58:61], v[220:223], v[232:235], v[58:61]
	v_mfma_f32_16x16x32_bf16 v[62:65], v[220:223], v[236:239], v[62:65]
	s_waitcnt lgkmcnt(3)
	v_mfma_f32_16x16x32_bf16 v[74:77], v[208:211], v[240:243], v[74:77]
	s_waitcnt lgkmcnt(2)
	v_mfma_f32_16x16x32_bf16 v[78:81], v[208:211], v[244:247], v[78:81]
	s_waitcnt lgkmcnt(1)
	v_mfma_f32_16x16x32_bf16 v[82:85], v[208:211], v[248:251], v[82:85]
	s_waitcnt lgkmcnt(0)
	v_mfma_f32_16x16x32_bf16 v[86:89], v[208:211], v[156:159], v[86:89]
	v_mfma_f32_16x16x32_bf16 v[90:93], v[212:215], v[240:243], v[90:93]
	v_mfma_f32_16x16x32_bf16 v[94:97], v[212:215], v[244:247], v[94:97]
	v_mfma_f32_16x16x32_bf16 v[98:101], v[212:215], v[248:251], v[98:101]
	v_mfma_f32_16x16x32_bf16 v[102:105], v[212:215], v[156:159], v[102:105]
	v_mfma_f32_16x16x32_bf16 v[106:109], v[216:219], v[240:243], v[106:109]
	v_mfma_f32_16x16x32_bf16 v[110:113], v[216:219], v[244:247], v[110:113]
	v_mfma_f32_16x16x32_bf16 v[114:117], v[216:219], v[248:251], v[114:117]
	v_mfma_f32_16x16x32_bf16 v[118:121], v[216:219], v[156:159], v[118:121]
	v_mfma_f32_16x16x32_bf16 v[122:125], v[220:223], v[240:243], v[122:125]
	v_mfma_f32_16x16x32_bf16 v[126:129], v[220:223], v[244:247], v[126:129]
	v_mfma_f32_16x16x32_bf16 v[130:133], v[220:223], v[248:251], v[130:133]
	v_mfma_f32_16x16x32_bf16 v[134:137], v[220:223], v[156:159], v[134:137]
	s_setprio 0
	s_barrier

; DI int TID() { int t = (int)__builtin_amdgcn_workitem_id_x(); asm volatile("" : "+v"(t)); return t; }
; #define BLOAD(A_, B_, kt) do { _Pragma("unroll") for (int i = 0; i < 4; ++i) { \
;     A_[i] = *(const u32x4*)((const char*)Ap + (aoff + (unsigned)(32 * i * lda + (kt) * 64) * 2u)); B_[i] = *(const u32x4*)((const char*)Wt + (woff + (unsigned)(32 * i * K + (kt) * 64) * 2u)); } } while (0)
; DI RowSS rowss_load(const float* ps, int m0) { const int tid = TID(); const float* q = ps + (size_t)(m0 + (tid >> 1)) * 16 + (tid & 1) * 8; RowSS r; r.a = *(const f32x4*)q; r.b = *(const f32x4*)(q + 4); return r; }
; #define BLOAD(A_, B_, kt) do { _Pragma("unroll") for (int i = 0; i < 4; ++i) { \
;     A_[i] = *(const u32x4*)((const char*)Ap + (aoff + (unsigned)(32 * i * lda + (kt) * 64) * 2u)); B_[i] = *(const u32x4*)((const char*)Wt + (woff + (unsigned)(32 * i * K + (kt) * 64) * 2u)); } } while (0)
; #define BSTORE(A_, B_, buf) do { _Pragma("unroll") for (int i = 0; i < 4; ++i) { \
;     *(u32x4*)&As[(buf) * GBUF + (srow + 32 * i) * LDT + sc8] = A_[i]; \
;     *(u32x4*)&Bs[(buf) * GBUF + (srow + 32 * i) * LDT + sc8] = B_[i]; } } while (0)
; template <int NK>
; DI void gemm_run(PF& pf, const u16* __restrict__ Ap, int lda, const u16* __restrict__ Wt, f32x16 (&acc)[2][2], char* smem) {
;   constexpr int K = NK * 64;
;   const int tid = TID(), lane = tid & 63, w = tid >> 6, wm = w >> 1, wn = w & 1, r32 = lane & 31, hi = lane >> 5;
;   u16* As = (u16*)smem; u16* Bs = As + 128 * LDT;
;   const int srow = tid >> 3, sc8 = (tid & 7) * 8;
;   constexpr int nk = NK;
;   const unsigned aoff = (unsigned)(srow * lda + sc8) * 2u, woff = (unsigned)(srow * K + sc8) * 2u;
;     ...
;   __builtin_amdgcn_s_setprio(0);
;   __syncthreads();
;   BSTORE(pf.a0, pf.b0, 0);
;   BLOAD(pf.a0, pf.b0, 2);
;   __syncthreads();
; DI void tile_inproj(const Params& p, int l, const Chunk& ck, int tile, int next, PF& pf, char* smem) {
;   float* Cs = (float*)smem; float* rinv_s = (float*)(smem + SMEM_CS);
;   const int mi = tile & (MTN - 1), nj = tile >> MTS; const int ni = (nj < 45) ? nj : 69; const int m0 = mi * 128;
;   const u16* Ap; const u16* Wt; inproj_ptrs(p, l, tile, Ap, Wt);
;   f32x16 acc[2][2]; zero_acc(acc);
;   const RowSS rss = rowss_load((const float*)(p.ws + OFF_PSIN), m0);
;   gemm_run<16>(pf, Ap, 1024, Wt, acc, smem);
.LBB1_384:
	s_mov_b32 s0, s16
	s_add_i32 s16, s16, s78
	s_cmpk_gt_i32 s16, 0x16ff
	s_cselect_b64 s[28:29], -1, 0
	s_cmpk_lt_i32 s16, 0x1700
	s_cselect_b32 s34, s16, -1
	s_ashr_i32 s0, s0, 7
	s_cmp_lt_i32 s0, 45
	s_cselect_b64 s[36:37], -1, 0
	s_and_b64 s[30:31], s[36:37], exec
	v_mov_b32_e32 v0, v172
	s_cselect_b32 s30, s0, 0x45
	s_and_b32 s79, s75, 0x3f80
	s_and_b32 s0, s43, 0xfe0000
	s_waitcnt lgkmcnt(0)
	v_ashrrev_i32_e32 v2, 1, v0
	v_add_u32_e32 v2, s79, v2
	v_ashrrev_i32_e32 v3, 31, v2
	v_lshlrev_b64 v[2:3], 6, v[2:3]
	v_lshlrev_b32_e32 v0, 5, v0
	v_lshl_add_u64 v[2:3], s[20:21], 0, v[2:3]
	v_and_b32_e32 v0, 32, v0
	v_lshl_add_u64 v[2:3], v[2:3], 0, v[0:1]
	global_load_dwordx4 v[130:133], v[2:3], off offset:16
	global_load_dwordx4 v[134:137], v[2:3], off
	s_lshl_b32 s0, s0, 1
	s_add_u32 s40, s17, s0
	s_addc_u32 s41, s42, 0
	s_ashr_i32 s31, s30, 31
	s_lshl_b64 s[56:57], s[30:31], 18
	s_add_u32 vcc_lo, s52, s56
	s_addc_u32 vcc_hi, s53, s57
	s_setprio 0
	s_waitcnt lgkmcnt(0)
	s_cmp_lg_u32 s14, 0
	s_cbranch_scc1 .Linp_pass1
	s_mov_b64 s[48:49], s[40:41]
	s_lshl_b32 s15, s30, 13
	s_add_u32 s50, s52, s15
	s_addc_u32 s51, s53, 0
	s_mov_b32 s13, 0x5a000
	v_and_b32_e32 v144, 63, v172
	v_lshrrev_b32_e32 v145, 6, v172
	v_bfe_u32 v146, v144, 4, 2
	v_lshrrev_b32_e32 v147, 1, v146
	v_xor_b32_e32 v146, v146, v147
	v_and_b32_e32 v146, 1, v146
	v_lshl_or_b32 v146, v146, 1, v147
	v_xor_b32_e32 v146, v146, v144
	v_and_b32_e32 v146, 3, v146
	v_lshlrev_b32_e32 v146, 4, v146
	v_lshrrev_b32_e32 v147, 2, v144
	v_lshl_add_u32 v138, v145, 5, v147
	v_lshl_add_u32 v138, v138, 11, v146
	v_add_u32_e32 v139, 0x7c00, v138
	v_lshl_add_u32 v140, v145, 6, v147
	v_lshl_add_u32 v140, v140, 6, v146
	v_mov_b32_e32 v141, v140
	v_mov_b32_e32 v142, v140
	v_mov_b32_e32 v143, v140
	v_readfirstlane_b32 s46, v145
	s_lshl_b32 s47, s46, 12
	s_lshl_b32 s46, s46, 11
	s_add_u32 s47, s47, 0x2000
	v_bfe_u32 v146, v144, 2, 2
	v_lshrrev_b32_e32 v147, 1, v146
	v_xor_b32_e32 v146, v146, v147
	v_and_b32_e32 v146, 1, v146
	v_lshl_or_b32 v146, v146, 1, v147
	v_lshrrev_b32_e32 v147, 4, v144
	v_xor_b32_e32 v146, v146, v147
	v_lshlrev_b32_e32 v146, 4, v146
	v_and_b32_e32 v144, 15, v144
	v_lshl_add_u32 v144, v144, 6, v146
	v_lshrrev_b32_e32 v146, 1, v145
	v_and_b32_e32 v147, 1, v145
	v_lshl_add_u32 v126, v146, 12, v144
	v_lshl_add_u32 v128, v147, 12, v144
	v_add_u32_e32 v128, 0x2000, v128
	s_cmp_eq_u32 s30, 44
	s_cselect_b32 s15, 1, 0
	s_cmp_ge_u32 s46, 0x1000
	s_cselect_b32 s15, s15, 0
	s_cmp_lg_u32 s15, 0
	s_cbranch_scc0 .Linp_nokr
	s_add_u32 s50, s52, 0x113e000
	s_addc_u32 s51, s53, 0
	s_mov_b32 s13, 0x2000
.Linp_nokr:
	s_barrier
	v_mov_b32_e32 v2, 0
	v_mov_b32_e32 v3, 0
	v_mov_b32_e32 v4, 0
	v_mov_b32_e32 v5, 0
	v_mov_b32_e32 v6, 0
	v_mov_b32_e32 v7, 0
	v_mov_b32_e32 v8, 0
	v_mov_b32_e32 v9, 0
	v_mov_b32_e32 v10, 0
	v_mov_b32_e32 v11, 0
	v_mov_b32_e32 v12, 0
	v_mov_b32_e32 v13, 0
	v_mov_b32_e32 v14, 0
	v_mov_b32_e32 v15, 0
	v_mov_b32_e32 v16, 0
	v_mov_b32_e32 v17, 0
	v_mov_b32_e32 v18, 0
	v_mov_b32_e32 v19, 0
	v_mov_b32_e32 v20, 0
	v_mov_b32_e32 v21, 0
	v_mov_b32_e32 v22, 0
	v_mov_b32_e32 v23, 0
	v_mov_b32_e32 v24, 0
	v_mov_b32_e32 v25, 0
	v_mov_b32_e32 v26, 0
	v_mov_b32_e32 v27, 0
	v_mov_b32_e32 v28, 0
	v_mov_b32_e32 v29, 0
	v_mov_b32_e32 v30, 0
	v_mov_b32_e32 v31, 0
	v_mov_b32_e32 v32, 0
	v_mov_b32_e32 v33, 0
	v_mov_b32_e32 v34, 0
	v_mov_b32_e32 v35, 0
	v_mov_b32_e32 v36, 0
	v_mov_b32_e32 v37, 0
	v_mov_b32_e32 v38, 0
	v_mov_b32_e32 v39, 0
	v_mov_b32_e32 v40, 0
	v_mov_b32_e32 v41, 0
	v_mov_b32_e32 v42, 0
	v_mov_b32_e32 v43, 0
	v_mov_b32_e32 v44, 0
	v_mov_b32_e32 v45, 0
	v_mov_b32_e32 v46, 0
	v_mov_b32_e32 v47, 0
	v_mov_b32_e32 v48, 0
	v_mov_b32_e32 v49, 0
	v_mov_b32_e32 v50, 0
	v_mov_b32_e32 v51, 0
	v_mov_b32_e32 v52, 0
	v_mov_b32_e32 v53, 0
	v_mov_b32_e32 v54, 0
	v_mov_b32_e32 v55, 0
	v_mov_b32_e32 v56, 0
	v_mov_b32_e32 v57, 0
	v_mov_b32_e32 v58, 0
	v_mov_b32_e32 v59, 0
	v_mov_b32_e32 v60, 0
	v_mov_b32_e32 v61, 0
	v_mov_b32_e32 v62, 0
	v_mov_b32_e32 v63, 0
	v_mov_b32_e32 v64, 0
	v_mov_b32_e32 v65, 0
	v_mov_b32_e32 v74, 0
	v_mov_b32_e32 v75, 0
	v_mov_b32_e32 v76, 0
	v_mov_b32_e32 v77, 0
	v_mov_b32_e32 v78, 0
	v_mov_b32_e32 v79, 0
	v_mov_b32_e32 v80, 0
	v_mov_b32_e32 v81, 0
	v_mov_b32_e32 v82, 0
	v_mov_b32_e32 v83, 0
	v_mov_b32_e32 v84, 0
	v_mov_b32_e32 v85, 0
	v_mov_b32_e32 v86, 0
	v_mov_b32_e32 v87, 0
	v_mov_b32_e32 v88, 0
	v_mov_b32_e32 v89, 0
	v_mov_b32_e32 v90, 0
	v_mov_b32_e32 v91, 0
	v_mov_b32_e32 v92, 0
	v_mov_b32_e32 v93, 0
	v_mov_b32_e32 v94, 0
	v_mov_b32_e32 v95, 0
	v_mov_b32_e32 v96, 0
	v_mov_b32_e32 v97, 0
	v_mov_b32_e32 v98, 0
	v_mov_b32_e32 v99, 0
	v_mov_b32_e32 v100, 0
	v_mov_b32_e32 v101, 0
	v_mov_b32_e32 v102, 0
	v_mov_b32_e32 v103, 0
	v_mov_b32_e32 v104, 0
	v_mov_b32_e32 v105, 0
	v_mov_b32_e32 v106, 0
	v_mov_b32_e32 v107, 0
	v_mov_b32_e32 v108, 0
	v_mov_b32_e32 v109, 0
	v_mov_b32_e32 v110, 0
	v_mov_b32_e32 v111, 0
	v_mov_b32_e32 v112, 0
	v_mov_b32_e32 v113, 0
	v_mov_b32_e32 v114, 0
	v_mov_b32_e32 v115, 0
	v_mov_b32_e32 v116, 0
	v_mov_b32_e32 v117, 0
	v_mov_b32_e32 v118, 0
	v_mov_b32_e32 v119, 0
	v_mov_b32_e32 v120, 0
	v_mov_b32_e32 v121, 0
	v_mov_b32_e32 v208, 0
	v_mov_b32_e32 v209, 0
	v_mov_b32_e32 v210, 0
	v_mov_b32_e32 v211, 0
	v_mov_b32_e32 v212, 0
	v_mov_b32_e32 v213, 0
	v_mov_b32_e32 v214, 0
	v_mov_b32_e32 v215, 0
	v_mov_b32_e32 v216, 0
	v_mov_b32_e32 v217, 0
	v_mov_b32_e32 v218, 0
	v_mov_b32_e32 v219, 0
	v_mov_b32_e32 v220, 0
	v_mov_b32_e32 v221, 0
	v_mov_b32_e32 v222, 0
	v_mov_b32_e32 v223, 0
	s_add_u32 m0, s46, 0x0
	s_nop 0
	global_load_lds_dwordx4 v138, s[48:49]
	global_load_lds_dwordx4 v139, s[48:49] offset:1024
	s_add_u32 m0, s47, 0x0
	s_nop 0
	global_load_lds_dwordx4 v140, s[50:51]
	global_load_lds_dwordx4 v141, s[50:51] offset:1024
	global_load_lds_dwordx4 v142, s[50:51] offset:2048
	global_load_lds_dwordx4 v143, s[50:51] offset:3072
	s_add_u32 m0, s46, 0x6000
	s_add_u32 s48, s48, 0x40
	s_addc_u32 s49, s49, 0
	global_load_lds_dwordx4 v138, s[48:49]
	global_load_lds_dwordx4 v139, s[48:49] offset:1024
	s_add_u32 m0, s47, 0x6000
	s_add_u32 s50, s50, s13
	s_addc_u32 s51, s51, 0
	global_load_lds_dwordx4 v140, s[50:51]
	global_load_lds_dwordx4 v141, s[50:51] offset:1024
	global_load_lds_dwordx4 v142, s[50:51] offset:2048
	global_load_lds_dwordx4 v143, s[50:51] offset:3072
	s_mov_b32 s12, 10
; #define BLOAD(A_, B_, kt) do { _Pragma("unroll") for (int i = 0; i < 4; ++i) { \
;     A_[i] = *(const u32x4*)((const char*)Ap + (aoff + (unsigned)(32 * i * lda + (kt) * 64) * 2u)); B_[i] = *(const u32x4*)((const char*)Wt + (woff + (unsigned)(32 * i * K + (kt) * 64) * 2u)); } } while (0)
; #define BLOAD(A_, B_, kt) do { _Pragma("unroll") for (int i = 0; i < 4; ++i) { \
;     A_[i] = *(const u32x4*)((const char*)Ap + (aoff + (unsigned)(32 * i * lda + (kt) * 64) * 2u)); B_[i] = *(const u32x4*)((const char*)Wt + (woff + (unsigned)(32 * i * K + (kt) * 64) * 2u)); } } while (0)
; #define BSTORE(A_, B_, buf) do { _Pragma("unroll") for (int i = 0; i < 4; ++i) { \
;     *(u32x4*)&As[(buf) * GBUF + (srow + 32 * i) * LDT + sc8] = A_[i]; \
;     *(u32x4*)&Bs[(buf) * GBUF + (srow + 32 * i) * LDT + sc8] = B_[i]; } } while (0)
; template <int NK>
; DI void gemm_run(PF& pf, const u16* __restrict__ Ap, int lda, const u16* __restrict__ Wt, f32x16 (&acc)[2][2], char* smem) {
;     ...
;   __builtin_amdgcn_s_setprio(0);
;   __syncthreads();
;   BSTORE(pf.a0, pf.b0, 0);
;   BLOAD(pf.a0, pf.b0, 2);
;   __syncthreads();
; #pragma unroll
;   for (int kt = 0; kt < nk; kt += 2) {
;     BCOMP(0);
;     BSTORE(pf.a1, pf.b1, 1);
;     if (kt + 3 < nk) BLOAD(pf.a1, pf.b1, kt + 3);
;     __syncthreads();
;     BCOMP(1);
;     if (kt + 2 < nk) { BSTORE(pf.a0, pf.b0, 0); if (kt + 4 < nk) BLOAD(pf.a0, pf.b0, kt + 4); }
;     __syncthreads();
.Linp_kloop:
	s_waitcnt vmcnt(6)
	s_barrier
	s_setprio 1
	ds_read_b128 v[224:227], v126 offset:0
	ds_read_b128 v[240:243], v128 offset:0
	ds_read_b128 v[244:247], v128 offset:1024
	ds_read_b128 v[248:251], v128 offset:2048
	ds_read_b128 v[156:159], v128 offset:3072
	ds_read_b128 v[228:231], v126 offset:1024
	ds_read_b128 v[232:235], v126 offset:2048
	ds_read_b128 v[236:239], v126 offset:3072
	ds_read_b128 v[160:163], v128 offset:8192
	ds_read_b128 v[164:167], v128 offset:9216
	ds_read_b128 v[168:171], v128 offset:10240
	ds_read_b128 v[122:125], v128 offset:11264
	s_add_u32 m0, s46, 0xc000
	s_add_u32 s48, s48, 0x40
	s_addc_u32 s49, s49, 0
	global_load_lds_dwordx4 v138, s[48:49]
	global_load_lds_dwordx4 v139, s[48:49] offset:1024
	s_add_u32 m0, s47, 0xc000
	s_add_u32 s50, s50, s13
	s_addc_u32 s51, s51, 0
	global_load_lds_dwordx4 v140, s[50:51]
	global_load_lds_dwordx4 v141, s[50:51] offset:1024
	global_load_lds_dwordx4 v142, s[50:51] offset:2048
	global_load_lds_dwordx4 v143, s[50:51] offset:3072
	s_waitcnt lgkmcnt(10)
	v_mfma_f32_16x16x32_bf16 v[2:5], v[224:227], v[240:243], v[2:5]
	s_waitcnt lgkmcnt(9)
	v_mfma_f32_16x16x32_bf16 v[6:9], v[224:227], v[244:247], v[6:9]
	s_waitcnt lgkmcnt(8)
	v_mfma_f32_16x16x32_bf16 v[10:13], v[224:227], v[248:251], v[10:13]
	s_waitcnt lgkmcnt(7)
	v_mfma_f32_16x16x32_bf16 v[14:17], v[224:227], v[156:159], v[14:17]
	s_waitcnt lgkmcnt(6)
	v_mfma_f32_16x16x32_bf16 v[18:21], v[228:231], v[240:243], v[18:21]
	v_mfma_f32_16x16x32_bf16 v[22:25], v[228:231], v[244:247], v[22:25]
	v_mfma_f32_16x16x32_bf16 v[26:29], v[228:231], v[248:251], v[26:29]
	v_mfma_f32_16x16x32_bf16 v[30:33], v[228:231], v[156:159], v[30:33]
	s_waitcnt lgkmcnt(5)
	v_mfma_f32_16x16x32_bf16 v[34:37], v[232:235], v[240:243], v[34:37]
	v_mfma_f32_16x16x32_bf16 v[38:41], v[232:235], v[244:247], v[38:41]
	v_mfma_f32_16x16x32_bf16 v[42:45], v[232:235], v[248:251], v[42:45]
	v_mfma_f32_16x16x32_bf16 v[46:49], v[232:235], v[156:159], v[46:49]
	s_waitcnt lgkmcnt(4)
	v_mfma_f32_16x16x32_bf16 v[50:53], v[236:239], v[240:243], v[50:53]
	v_mfma_f32_16x16x32_bf16 v[54:57], v[236:239], v[244:247], v[54:57]
	v_mfma_f32_16x16x32_bf16 v[58:61], v[236:239], v[248:251], v[58:61]
	v_mfma_f32_16x16x32_bf16 v[62:65], v[236:239], v[156:159], v[62:65]
	s_waitcnt lgkmcnt(3)
	v_mfma_f32_16x16x32_bf16 v[74:77], v[224:227], v[160:163], v[74:77]
	s_waitcnt lgkmcnt(2)
	v_mfma_f32_16x16x32_bf16 v[78:81], v[224:227], v[164:167], v[78:81]
	s_waitcnt lgkmcnt(1)
	v_mfma_f32_16x16x32_bf16 v[82:85], v[224:227], v[168:171], v[82:85]
	s_waitcnt lgkmcnt(0)
	v_mfma_f32_16x16x32_bf16 v[86:89], v[224:227], v[122:125], v[86:89]
	v_mfma_f32_16x16x32_bf16 v[90:93], v[228:231], v[160:163], v[90:93]
	v_mfma_f32_16x16x32_bf16 v[94:97], v[228:231], v[164:167], v[94:97]
	v_mfma_f32_16x16x32_bf16 v[98:101], v[228:231], v[168:171], v[98:101]
	v_mfma_f32_16x16x32_bf16 v[102:105], v[228:231], v[122:125], v[102:105]
	v_mfma_f32_16x16x32_bf16 v[106:109], v[232:235], v[160:163], v[106:109]
	v_mfma_f32_16x16x32_bf16 v[110:113], v[232:235], v[164:167], v[110:113]
	v_mfma_f32_16x16x32_bf16 v[114:117], v[232:235], v[168:171], v[114:117]
	v_mfma_f32_16x16x32_bf16 v[118:121], v[232:235], v[122:125], v[118:121]
	v_mfma_f32_16x16x32_bf16 v[208:211], v[236:239], v[160:163], v[208:211]
	v_mfma_f32_16x16x32_bf16 v[212:215], v[236:239], v[164:167], v[212:215]
	v_mfma_f32_16x16x32_bf16 v[216:219], v[236:239], v[168:171], v[216:219]
	v_mfma_f32_16x16x32_bf16 v[220:223], v[236:239], v[122:125], v[220:223]
	s_setprio 0
	s_waitcnt vmcnt(6)
	s_barrier
	s_setprio 1
	ds_read_b128 v[224:227], v126 offset:24576
	ds_read_b128 v[240:243], v128 offset:24576
	ds_read_b128 v[244:247], v128 offset:25600
	ds_read_b128 v[248:251], v128 offset:26624
	ds_read_b128 v[156:159], v128 offset:27648
	ds_read_b128 v[228:231], v126 offset:25600
	ds_read_b128 v[232:235], v126 offset:26624
	ds_read_b128 v[236:239], v126 offset:27648
	ds_read_b128 v[160:163], v128 offset:32768
	ds_read_b128 v[164:167], v128 offset:33792
	ds_read_b128 v[168:171], v128 offset:34816
	ds_read_b128 v[122:125], v128 offset:35840
	s_add_u32 m0, s46, 0x0
	s_add_u32 s48, s48, 0x40
	s_addc_u32 s49, s49, 0
	global_load_lds_dwordx4 v138, s[48:49]
	global_load_lds_dwordx4 v139, s[48:49] offset:1024
	s_add_u32 m0, s47, 0x0
	s_add_u32 s50, s50, s13
	s_addc_u32 s51, s51, 0
	global_load_lds_dwordx4 v140, s[50:51]
	global_load_lds_dwordx4 v141, s[50:51] offset:1024
	global_load_lds_dwordx4 v142, s[50:51] offset:2048
	global_load_lds_dwordx4 v143, s[50:51] offset:3072
	s_waitcnt lgkmcnt(10)
	v_mfma_f32_16x16x32_bf16 v[2:5], v[224:227], v[240:243], v[2:5]
	s_waitcnt lgkmcnt(9)
	v_mfma_f32_16x16x32_bf16 v[6:9], v[224:227], v[244:247], v[6:9]
	s_waitcnt lgkmcnt(8)
	v_mfma_f32_16x16x32_bf16 v[10:13], v[224:227], v[248:251], v[10:13]
	s_waitcnt lgkmcnt(7)
	v_mfma_f32_16x16x32_bf16 v[14:17], v[224:227], v[156:159], v[14:17]
	s_waitcnt lgkmcnt(6)
	v_mfma_f32_16x16x32_bf16 v[18:21], v[228:231], v[240:243], v[18:21]
	v_mfma_f32_16x16x32_bf16 v[22:25], v[228:231], v[244:247], v[22:25]
	v_mfma_f32_16x16x32_bf16 v[26:29], v[228:231], v[248:251], v[26:29]
	v_mfma_f32_16x16x32_bf16 v[30:33], v[228:231], v[156:159], v[30:33]
	s_waitcnt lgkmcnt(5)
	v_mfma_f32_16x16x32_bf16 v[34:37], v[232:235], v[240:243], v[34:37]
	v_mfma_f32_16x16x32_bf16 v[38:41], v[232:235], v[244:247], v[38:41]
	v_mfma_f32_16x16x32_bf16 v[42:45], v[232:235], v[248:251], v[42:45]
	v_mfma_f32_16x16x32_bf16 v[46:49], v[232:235], v[156:159], v[46:49]
	s_waitcnt lgkmcnt(4)
	v_mfma_f32_16x16x32_bf16 v[50:53], v[236:239], v[240:243], v[50:53]
	v_mfma_f32_16x16x32_bf16 v[54:57], v[236:239], v[244:247], v[54:57]
	v_mfma_f32_16x16x32_bf16 v[58:61], v[236:239], v[248:251], v[58:61]
	v_mfma_f32_16x16x32_bf16 v[62:65], v[236:239], v[156:159], v[62:65]
	s_waitcnt lgkmcnt(3)
	v_mfma_f32_16x16x32_bf16 v[74:77], v[224:227], v[160:163], v[74:77]
	s_waitcnt lgkmcnt(2)
	v_mfma_f32_16x16x32_bf16 v[78:81], v[224:227], v[164:167], v[78:81]
	s_waitcnt lgkmcnt(1)
	v_mfma_f32_16x16x32_bf16 v[82:85], v[224:227], v[168:171], v[82:85]
	s_waitcnt lgkmcnt(0)
	v_mfma_f32_16x16x32_bf16 v[86:89], v[224:227], v[122:125], v[86:89]
	v_mfma_f32_16x16x32_bf16 v[90:93], v[228:231], v[160:163], v[90:93]
	v_mfma_f32_16x16x32_bf16 v[94:97], v[228:231], v[164:167], v[94:97]
	v_mfma_f32_16x16x32_bf16 v[98:101], v[228:231], v[168:171], v[98:101]
	v_mfma_f32_16x16x32_bf16 v[102:105], v[228:231], v[122:125], v[102:105]
	v_mfma_f32_16x16x32_bf16 v[106:109], v[232:235], v[160:163], v[106:109]
	v_mfma_f32_16x16x32_bf16 v[110:113], v[232:235], v[164:167], v[110:113]
	v_mfma_f32_16x16x32_bf16 v[114:117], v[232:235], v[168:171], v[114:117]
	v_mfma_f32_16x16x32_bf16 v[118:121], v[232:235], v[122:125], v[118:121]
	v_mfma_f32_16x16x32_bf16 v[208:211], v[236:239], v[160:163], v[208:211]
	v_mfma_f32_16x16x32_bf16 v[212:215], v[236:239], v[164:167], v[212:215]
	v_mfma_f32_16x16x32_bf16 v[216:219], v[236:239], v[168:171], v[216:219]
	v_mfma_f32_16x16x32_bf16 v[220:223], v[236:239], v[122:125], v[220:223]
	s_setprio 0
	s_waitcnt vmcnt(6)
	s_barrier
; #define BLOAD(A_, B_, kt) do { _Pragma("unroll") for (int i = 0; i < 4; ++i) { \
;     A_[i] = *(const u32x4*)((const char*)Ap + (aoff + (unsigned)(32 * i * lda + (kt) * 64) * 2u)); B_[i] = *(const u32x4*)((const char*)Wt + (woff + (unsigned)(32 * i * K + (kt) * 64) * 2u)); } } while (0)
; #define BLOAD(A_, B_, kt) do { _Pragma("unroll") for (int i = 0; i < 4; ++i) { \
;     A_[i] = *(const u32x4*)((const char*)Ap + (aoff + (unsigned)(32 * i * lda + (kt) * 64) * 2u)); B_[i] = *(const u32x4*)((const char*)Wt + (woff + (unsigned)(32 * i * K + (kt) * 64) * 2u)); } } while (0)
; #define BSTORE(A_, B_, buf) do { _Pragma("unroll") for (int i = 0; i < 4; ++i) { \
;     *(u32x4*)&As[(buf) * GBUF + (srow + 32 * i) * LDT + sc8] = A_[i]; \
;     *(u32x4*)&Bs[(buf) * GBUF + (srow + 32 * i) * LDT + sc8] = B_[i]; } } while (0)
; template <int NK>
; DI void gemm_run(PF& pf, const u16* __restrict__ Ap, int lda, const u16* __restrict__ Wt, f32x16 (&acc)[2][2], char* smem) {
;     ...
;   __builtin_amdgcn_s_setprio(0);
;   __syncthreads();
;   BSTORE(pf.a0, pf.b0, 0);
;   BLOAD(pf.a0, pf.b0, 2);
;   __syncthreads();
; #pragma unroll
;   for (int kt = 0; kt < nk; kt += 2) {
;     BCOMP(0);
;     BSTORE(pf.a1, pf.b1, 1);
;     if (kt + 3 < nk) BLOAD(pf.a1, pf.b1, kt + 3);
;     __syncthreads();
;     BCOMP(1);
;     if (kt + 2 < nk) { BSTORE(pf.a0, pf.b0, 0); if (kt + 4 < nk) BLOAD(pf.a0, pf.b0, kt + 4); }
;     __syncthreads();
	s_setprio 1
	ds_read_b128 v[224:227], v126 offset:49152
	ds_read_b128 v[240:243], v128 offset:49152
	ds_read_b128 v[244:247], v128 offset:50176
	ds_read_b128 v[248:251], v128 offset:51200
	ds_read_b128 v[156:159], v128 offset:52224
	ds_read_b128 v[228:231], v126 offset:50176
	ds_read_b128 v[232:235], v126 offset:51200
	ds_read_b128 v[236:239], v126 offset:52224
	ds_read_b128 v[160:163], v128 offset:57344
	ds_read_b128 v[164:167], v128 offset:58368
	ds_read_b128 v[168:171], v128 offset:59392
	ds_read_b128 v[122:125], v128 offset:60416
	s_add_u32 m0, s46, 0x6000
	s_add_u32 s48, s48, 0x40
	s_addc_u32 s49, s49, 0
	global_load_lds_dwordx4 v138, s[48:49]
	global_load_lds_dwordx4 v139, s[48:49] offset:1024
	s_add_u32 m0, s47, 0x6000
	s_add_u32 s50, s50, s13
	s_addc_u32 s51, s51, 0
	global_load_lds_dwordx4 v140, s[50:51]
	global_load_lds_dwordx4 v141, s[50:51] offset:1024
	global_load_lds_dwordx4 v142, s[50:51] offset:2048
	global_load_lds_dwordx4 v143, s[50:51] offset:3072
	s_waitcnt lgkmcnt(10)
	v_mfma_f32_16x16x32_bf16 v[2:5], v[224:227], v[240:243], v[2:5]
	s_waitcnt lgkmcnt(9)
	v_mfma_f32_16x16x32_bf16 v[6:9], v[224:227], v[244:247], v[6:9]
	s_waitcnt lgkmcnt(8)
	v_mfma_f32_16x16x32_bf16 v[10:13], v[224:227], v[248:251], v[10:13]
	s_waitcnt lgkmcnt(7)
	v_mfma_f32_16x16x32_bf16 v[14:17], v[224:227], v[156:159], v[14:17]
	s_waitcnt lgkmcnt(6)
	v_mfma_f32_16x16x32_bf16 v[18:21], v[228:231], v[240:243], v[18:21]
	v_mfma_f32_16x16x32_bf16 v[22:25], v[228:231], v[244:247], v[22:25]
	v_mfma_f32_16x16x32_bf16 v[26:29], v[228:231], v[248:251], v[26:29]
	v_mfma_f32_16x16x32_bf16 v[30:33], v[228:231], v[156:159], v[30:33]
	s_waitcnt lgkmcnt(5)
	v_mfma_f32_16x16x32_bf16 v[34:37], v[232:235], v[240:243], v[34:37]
	v_mfma_f32_16x16x32_bf16 v[38:41], v[232:235], v[244:247], v[38:41]
	v_mfma_f32_16x16x32_bf16 v[42:45], v[232:235], v[248:251], v[42:45]
	v_mfma_f32_16x16x32_bf16 v[46:49], v[232:235], v[156:159], v[46:49]
	s_waitcnt lgkmcnt(4)
	v_mfma_f32_16x16x32_bf16 v[50:53], v[236:239], v[240:243], v[50:53]
	v_mfma_f32_16x16x32_bf16 v[54:57], v[236:239], v[244:247], v[54:57]
	v_mfma_f32_16x16x32_bf16 v[58:61], v[236:239], v[248:251], v[58:61]
	v_mfma_f32_16x16x32_bf16 v[62:65], v[236:239], v[156:159], v[62:65]
	s_waitcnt lgkmcnt(3)
	v_mfma_f32_16x16x32_bf16 v[74:77], v[224:227], v[160:163], v[74:77]
	s_waitcnt lgkmcnt(2)
	v_mfma_f32_16x16x32_bf16 v[78:81], v[224:227], v[164:167], v[78:81]
	s_waitcnt lgkmcnt(1)
	v_mfma_f32_16x16x32_bf16 v[82:85], v[224:227], v[168:171], v[82:85]
	s_waitcnt lgkmcnt(0)
	v_mfma_f32_16x16x32_bf16 v[86:89], v[224:227], v[122:125], v[86:89]
	v_mfma_f32_16x16x32_bf16 v[90:93], v[228:231], v[160:163], v[90:93]
	v_mfma_f32_16x16x32_bf16 v[94:97], v[228:231], v[164:167], v[94:97]
	v_mfma_f32_16x16x32_bf16 v[98:101], v[228:231], v[168:171], v[98:101]
	v_mfma_f32_16x16x32_bf16 v[102:105], v[228:231], v[122:125], v[102:105]
	v_mfma_f32_16x16x32_bf16 v[106:109], v[232:235], v[160:163], v[106:109]
	v_mfma_f32_16x16x32_bf16 v[110:113], v[232:235], v[164:167], v[110:113]
	v_mfma_f32_16x16x32_bf16 v[114:117], v[232:235], v[168:171], v[114:117]
	v_mfma_f32_16x16x32_bf16 v[118:121], v[232:235], v[122:125], v[118:121]
	v_mfma_f32_16x16x32_bf16 v[208:211], v[236:239], v[160:163], v[208:211]
	v_mfma_f32_16x16x32_bf16 v[212:215], v[236:239], v[164:167], v[212:215]
	v_mfma_f32_16x16x32_bf16 v[216:219], v[236:239], v[168:171], v[216:219]
	v_mfma_f32_16x16x32_bf16 v[220:223], v[236:239], v[122:125], v[220:223]
	s_setprio 0
	s_sub_u32 s12, s12, 1
	s_cmp_lg_u32 s12, 0
	s_cbranch_scc1 .Linp_kloop
	s_waitcnt vmcnt(6)
	s_barrier
; #define BLOAD(A_, B_, kt) do { _Pragma("unroll") for (int i = 0; i < 4; ++i) { \
;     A_[i] = *(const u32x4*)((const char*)Ap + (aoff + (unsigned)(32 * i * lda + (kt) * 64) * 2u)); B_[i] = *(const u32x4*)((const char*)Wt + (woff + (unsigned)(32 * i * K + (kt) * 64) * 2u)); } } while (0)
; #define BLOAD(A_, B_, kt) do { _Pragma("unroll") for (int i = 0; i < 4; ++i) { \
;     A_[i] = *(const u32x4*)((const char*)Ap + (aoff + (unsigned)(32 * i * lda + (kt) * 64) * 2u)); B_[i] = *(const u32x4*)((const char*)Wt + (woff + (unsigned)(32 * i * K + (kt) * 64) * 2u)); } } while (0)
; #define BSTORE(A_, B_, buf) do { _Pragma("unroll") for (int i = 0; i < 4; ++i) { \
;     *(u32x4*)&As[(buf) * GBUF + (srow + 32 * i) * LDT + sc8] = A_[i]; \
;     *(u32x4*)&Bs[(buf) * GBUF + (srow + 32 * i) * LDT + sc8] = B_[i]; } } while (0)
; template <int NK>
; DI void gemm_run(PF& pf, const u16* __restrict__ Ap, int lda, const u16* __restrict__ Wt, f32x16 (&acc)[2][2], char* smem) {
;     ...
; #pragma unroll
;   for (int kt = 0; kt < nk; kt += 2) {
;     BCOMP(0);
;     BSTORE(pf.a1, pf.b1, 1);
;     if (kt + 3 < nk) BLOAD(pf.a1, pf.b1, kt + 3);
;     __syncthreads();
;     BCOMP(1);
;     if (kt + 2 < nk) { BSTORE(pf.a0, pf.b0, 0); if (kt + 4 < nk) BLOAD(pf.a0, pf.b0, kt + 4); }
;     __syncthreads();
;   }
	s_setprio 1
	ds_read_b128 v[224:227], v126 offset:0
	ds_read_b128 v[240:243], v128 offset:0
	ds_read_b128 v[244:247], v128 offset:1024
	ds_read_b128 v[248:251], v128 offset:2048
	ds_read_b128 v[156:159], v128 offset:3072
	ds_read_b128 v[228:231], v126 offset:1024
	ds_read_b128 v[232:235], v126 offset:2048
	ds_read_b128 v[236:239], v126 offset:3072
	ds_read_b128 v[160:163], v128 offset:8192
	ds_read_b128 v[164:167], v128 offset:9216
	ds_read_b128 v[168:171], v128 offset:10240
	ds_read_b128 v[122:125], v128 offset:11264
	s_waitcnt lgkmcnt(10)
	v_mfma_f32_16x16x32_bf16 v[2:5], v[224:227], v[240:243], v[2:5]
	s_waitcnt lgkmcnt(9)
	v_mfma_f32_16x16x32_bf16 v[6:9], v[224:227], v[244:247], v[6:9]
	s_waitcnt lgkmcnt(8)
	v_mfma_f32_16x16x32_bf16 v[10:13], v[224:227], v[248:251], v[10:13]
	s_waitcnt lgkmcnt(7)
	v_mfma_f32_16x16x32_bf16 v[14:17], v[224:227], v[156:159], v[14:17]
	s_waitcnt lgkmcnt(6)
	v_mfma_f32_16x16x32_bf16 v[18:21], v[228:231], v[240:243], v[18:21]
	v_mfma_f32_16x16x32_bf16 v[22:25], v[228:231], v[244:247], v[22:25]
	v_mfma_f32_16x16x32_bf16 v[26:29], v[228:231], v[248:251], v[26:29]
	v_mfma_f32_16x16x32_bf16 v[30:33], v[228:231], v[156:159], v[30:33]
	s_waitcnt lgkmcnt(5)
	v_mfma_f32_16x16x32_bf16 v[34:37], v[232:235], v[240:243], v[34:37]
	v_mfma_f32_16x16x32_bf16 v[38:41], v[232:235], v[244:247], v[38:41]
	v_mfma_f32_16x16x32_bf16 v[42:45], v[232:235], v[248:251], v[42:45]
	v_mfma_f32_16x16x32_bf16 v[46:49], v[232:235], v[156:159], v[46:49]
	s_waitcnt lgkmcnt(4)
	v_mfma_f32_16x16x32_bf16 v[50:53], v[236:239], v[240:243], v[50:53]
	v_mfma_f32_16x16x32_bf16 v[54:57], v[236:239], v[244:247], v[54:57]
	v_mfma_f32_16x16x32_bf16 v[58:61], v[236:239], v[248:251], v[58:61]
	v_mfma_f32_16x16x32_bf16 v[62:65], v[236:239], v[156:159], v[62:65]
	s_waitcnt lgkmcnt(3)
	v_mfma_f32_16x16x32_bf16 v[74:77], v[224:227], v[160:163], v[74:77]
	s_waitcnt lgkmcnt(2)
	v_mfma_f32_16x16x32_bf16 v[78:81], v[224:227], v[164:167], v[78:81]
	s_waitcnt lgkmcnt(1)
	v_mfma_f32_16x16x32_bf16 v[82:85], v[224:227], v[168:171], v[82:85]
	s_waitcnt lgkmcnt(0)
	v_mfma_f32_16x16x32_bf16 v[86:89], v[224:227], v[122:125], v[86:89]
	v_mfma_f32_16x16x32_bf16 v[90:93], v[228:231], v[160:163], v[90:93]
	v_mfma_f32_16x16x32_bf16 v[94:97], v[228:231], v[164:167], v[94:97]
	v_mfma_f32_16x16x32_bf16 v[98:101], v[228:231], v[168:171], v[98:101]
	v_mfma_f32_16x16x32_bf16 v[102:105], v[228:231], v[122:125], v[102:105]
	v_mfma_f32_16x16x32_bf16 v[106:109], v[232:235], v[160:163], v[106:109]
	v_mfma_f32_16x16x32_bf16 v[110:113], v[232:235], v[164:167], v[110:113]
	v_mfma_f32_16x16x32_bf16 v[114:117], v[232:235], v[168:171], v[114:117]
	v_mfma_f32_16x16x32_bf16 v[118:121], v[232:235], v[122:125], v[118:121]
	v_mfma_f32_16x16x32_bf16 v[208:211], v[236:239], v[160:163], v[208:211]
	v_mfma_f32_16x16x32_bf16 v[212:215], v[236:239], v[164:167], v[212:215]
	v_mfma_f32_16x16x32_bf16 v[216:219], v[236:239], v[168:171], v[216:219]
	v_mfma_f32_16x16x32_bf16 v[220:223], v[236:239], v[122:125], v[220:223]
	s_setprio 0
	s_waitcnt vmcnt(0)
	s_barrier
	s_setprio 1
	ds_read_b128 v[224:227], v126 offset:24576
	ds_read_b128 v[240:243], v128 offset:24576
	ds_read_b128 v[244:247], v128 offset:25600
	ds_read_b128 v[248:251], v128 offset:26624
	ds_read_b128 v[156:159], v128 offset:27648
	ds_read_b128 v[228:231], v126 offset:25600
	ds_read_b128 v[232:235], v126 offset:26624
	ds_read_b128 v[236:239], v126 offset:27648
	ds_read_b128 v[160:163], v128 offset:32768
	ds_read_b128 v[164:167], v128 offset:33792
	ds_read_b128 v[168:171], v128 offset:34816
	ds_read_b128 v[122:125], v128 offset:35840
	s_waitcnt lgkmcnt(10)
	v_mfma_f32_16x16x32_bf16 v[2:5], v[224:227], v[240:243], v[2:5]
	s_waitcnt lgkmcnt(9)
	v_mfma_f32_16x16x32_bf16 v[6:9], v[224:227], v[244:247], v[6:9]
	s_waitcnt lgkmcnt(8)
	v_mfma_f32_16x16x32_bf16 v[10:13], v[224:227], v[248:251], v[10:13]
	s_waitcnt lgkmcnt(7)
	v_mfma_f32_16x16x32_bf16 v[14:17], v[224:227], v[156:159], v[14:17]
	s_waitcnt lgkmcnt(6)
	v_mfma_f32_16x16x32_bf16 v[18:21], v[228:231], v[240:243], v[18:21]
	v_mfma_f32_16x16x32_bf16 v[22:25], v[228:231], v[244:247], v[22:25]
	v_mfma_f32_16x16x32_bf16 v[26:29], v[228:231], v[248:251], v[26:29]
	v_mfma_f32_16x16x32_bf16 v[30:33], v[228:231], v[156:159], v[30:33]
	s_waitcnt lgkmcnt(5)
	v_mfma_f32_16x16x32_bf16 v[34:37], v[232:235], v[240:243], v[34:37]
	v_mfma_f32_16x16x32_bf16 v[38:41], v[232:235], v[244:247], v[38:41]
	v_mfma_f32_16x16x32_bf16 v[42:45], v[232:235], v[248:251], v[42:45]
	v_mfma_f32_16x16x32_bf16 v[46:49], v[232:235], v[156:159], v[46:49]
	s_waitcnt lgkmcnt(4)
	v_mfma_f32_16x16x32_bf16 v[50:53], v[236:239], v[240:243], v[50:53]
	v_mfma_f32_16x16x32_bf16 v[54:57], v[236:239], v[244:247], v[54:57]
	v_mfma_f32_16x16x32_bf16 v[58:61], v[236:239], v[248:251], v[58:61]
	v_mfma_f32_16x16x32_bf16 v[62:65], v[236:239], v[156:159], v[62:65]
	s_waitcnt lgkmcnt(3)
	v_mfma_f32_16x16x32_bf16 v[74:77], v[224:227], v[160:163], v[74:77]
	s_waitcnt lgkmcnt(2)
	v_mfma_f32_16x16x32_bf16 v[78:81], v[224:227], v[164:167], v[78:81]
	s_waitcnt lgkmcnt(1)
	v_mfma_f32_16x16x32_bf16 v[82:85], v[224:227], v[168:171], v[82:85]
	s_waitcnt lgkmcnt(0)
	v_mfma_f32_16x16x32_bf16 v[86:89], v[224:227], v[122:125], v[86:89]
	v_mfma_f32_16x16x32_bf16 v[90:93], v[228:231], v[160:163], v[90:93]
	v_mfma_f32_16x16x32_bf16 v[94:97], v[228:231], v[164:167], v[94:97]
	v_mfma_f32_16x16x32_bf16 v[98:101], v[228:231], v[168:171], v[98:101]
	v_mfma_f32_16x16x32_bf16 v[102:105], v[228:231], v[122:125], v[102:105]
	v_mfma_f32_16x16x32_bf16 v[106:109], v[232:235], v[160:163], v[106:109]
	v_mfma_f32_16x16x32_bf16 v[110:113], v[232:235], v[164:167], v[110:113]
	v_mfma_f32_16x16x32_bf16 v[114:117], v[232:235], v[168:171], v[114:117]
	v_mfma_f32_16x16x32_bf16 v[118:121], v[232:235], v[122:125], v[118:121]
	v_mfma_f32_16x16x32_bf16 v[208:211], v[236:239], v[160:163], v[208:211]
	v_mfma_f32_16x16x32_bf16 v[212:215], v[236:239], v[164:167], v[212:215]
	v_mfma_f32_16x16x32_bf16 v[216:219], v[236:239], v[168:171], v[216:219]
	v_mfma_f32_16x16x32_bf16 v[220:223], v[236:239], v[122:125], v[220:223]
	s_setprio 0
	s_barrier
	s_branch .Linp_post
.Linp_pass1:
	s_waitcnt vmcnt(0)
	s_barrier

; DI int TID() { int t = (int)__builtin_amdgcn_workitem_id_x(); asm volatile("" : "+v"(t)); return t; }
; DI int crow(int r, int hi) { return (r & 3) + 8 * (r >> 2) + 4 * hi; }
; DI void acc_to_cs(const f32x16 (&acc)[2][2], float* Cs) {
;   __builtin_amdgcn_s_setprio(2);
;   const int tid = TID(), lane = tid & 63, w = tid >> 6, wm = w >> 1, wn = w & 1, r32 = lane & 31, hi = lane >> 5;
; #pragma unroll
;   for (int mt = 0; mt < 2; ++mt)
; #pragma unroll
;     for (int nt = 0; nt < 2; ++nt)
; #pragma unroll
;       for (int r = 0; r < 16; ++r) Cs[(wm * 64 + mt * 32 + crow(r, hi)) * CSL + wn * 64 + nt * 32 + r32] = acc[mt][nt][r];
;   __syncthreads();
.LBB1_388:
	s_or_b64 exec, exec, s[34:35]
	v_and_b32_e32 v224, 63, v172
	v_lshrrev_b32_e32 v225, 6, v172
	v_lshrrev_b32_e32 v226, 4, v224
	v_lshlrev_b32_e32 v226, 2, v226
	v_lshrrev_b32_e32 v227, 1, v225
	v_lshl_add_u32 v226, v227, 6, v226
	v_mul_u32_u24_e32 v226, 0x84, v226
	v_and_b32_e32 v227, 1, v225
	v_and_b32_e32 v224, 15, v224
	v_lshl_add_u32 v224, v227, 6, v224
	v_add_lshl_u32 v226, v226, v224, 2
	s_cmp_lg_u32 s14, 0
	s_cbranch_scc1 .Linp_w1
	ds_write_b32 v226, v2 offset:0
	ds_write_b32 v226, v3 offset:528
	ds_write_b32 v226, v4 offset:1056
	ds_write_b32 v226, v5 offset:1584
	ds_write_b32 v226, v6 offset:64
	ds_write_b32 v226, v7 offset:592
	ds_write_b32 v226, v8 offset:1120
	ds_write_b32 v226, v9 offset:1648
	ds_write_b32 v226, v10 offset:128
	ds_write_b32 v226, v11 offset:656
	ds_write_b32 v226, v12 offset:1184
	ds_write_b32 v226, v13 offset:1712
	ds_write_b32 v226, v14 offset:192
	ds_write_b32 v226, v15 offset:720
	ds_write_b32 v226, v16 offset:1248
	ds_write_b32 v226, v17 offset:1776
	ds_write_b32 v226, v18 offset:8448
	ds_write_b32 v226, v19 offset:8976
	ds_write_b32 v226, v20 offset:9504
	ds_write_b32 v226, v21 offset:10032
	ds_write_b32 v226, v22 offset:8512
	ds_write_b32 v226, v23 offset:9040
	ds_write_b32 v226, v24 offset:9568
	ds_write_b32 v226, v25 offset:10096
	ds_write_b32 v226, v26 offset:8576
	ds_write_b32 v226, v27 offset:9104
	ds_write_b32 v226, v28 offset:9632
	ds_write_b32 v226, v29 offset:10160
	ds_write_b32 v226, v30 offset:8640
	ds_write_b32 v226, v31 offset:9168
	ds_write_b32 v226, v32 offset:9696
	ds_write_b32 v226, v33 offset:10224
	ds_write_b32 v226, v34 offset:16896
	ds_write_b32 v226, v35 offset:17424
	ds_write_b32 v226, v36 offset:17952
	ds_write_b32 v226, v37 offset:18480
	ds_write_b32 v226, v38 offset:16960
	ds_write_b32 v226, v39 offset:17488
	ds_write_b32 v226, v40 offset:18016
	ds_write_b32 v226, v41 offset:18544
	ds_write_b32 v226, v42 offset:17024
	ds_write_b32 v226, v43 offset:17552
	ds_write_b32 v226, v44 offset:18080
	ds_write_b32 v226, v45 offset:18608
	ds_write_b32 v226, v46 offset:17088
	ds_write_b32 v226, v47 offset:17616
	ds_write_b32 v226, v48 offset:18144
	ds_write_b32 v226, v49 offset:18672
	ds_write_b32 v226, v50 offset:25344
	ds_write_b32 v226, v51 offset:25872
	ds_write_b32 v226, v52 offset:26400
	ds_write_b32 v226, v53 offset:26928
	ds_write_b32 v226, v54 offset:25408
	ds_write_b32 v226, v55 offset:25936
	ds_write_b32 v226, v56 offset:26464
	ds_write_b32 v226, v57 offset:26992
	ds_write_b32 v226, v58 offset:25472
	ds_write_b32 v226, v59 offset:26000
	ds_write_b32 v226, v60 offset:26528
	ds_write_b32 v226, v61 offset:27056
	ds_write_b32 v226, v62 offset:25536
	ds_write_b32 v226, v63 offset:26064
	ds_write_b32 v226, v64 offset:26592
	ds_write_b32 v226, v65 offset:27120
	s_branch .Linp_wd

; DI int TID() { int t = (int)__builtin_amdgcn_workitem_id_x(); asm volatile("" : "+v"(t)); return t; }
; DI int crow(int r, int hi) { return (r & 3) + 8 * (r >> 2) + 4 * hi; }
; DI void acc_to_cs(const f32x16 (&acc)[2][2], float* Cs) {
;   __builtin_amdgcn_s_setprio(2);
;   const int tid = TID(), lane = tid & 63, w = tid >> 6, wm = w >> 1, wn = w & 1, r32 = lane & 31, hi = lane >> 5;
; #pragma unroll
;   for (int mt = 0; mt < 2; ++mt)
; #pragma unroll
;     for (int nt = 0; nt < 2; ++nt)
; #pragma unroll
;       for (int r = 0; r < 16; ++r) Cs[(wm * 64 + mt * 32 + crow(r, hi)) * CSL + wn * 64 + nt * 32 + r32] = acc[mt][nt][r];
;   __syncthreads();
; DI void tile_inproj(const Params& p, int l, const Chunk& ck, int tile, int next, PF& pf, char* smem) {
;     ...
;   const int tid = TID(), row = tid >> 1, half = tid & 1;
;   const int lt = m0 + row; const int S = ck.S; const int bl = lt >> ck.sshift, t = lt & (S - 1);
;   const float rinv = rinv_s[row];
;   float v[8];
;   if (ni < 24 || (ni >= 41 && ni < 45)) {
.Linp_wd:
	s_setprio 2
	v_mov_b32_e32 v0, v172
	s_cmp_gt_i32 s30, 23
	v_lshrrev_b32_e32 v131, 1, v0
	v_and_b32_e32 v131, 0xfffffc0, v131
	s_waitcnt lgkmcnt(0)
	v_lshrrev_b32_e32 v132, 3, v0
	v_and_or_b32 v131, v132, 4, v131
	v_and_b32_e32 v0, 0x5f, v0
	v_mul_lo_u32 v131, v131, s5
	v_lshl_add_u32 v0, v0, 2, v131
	v_add_u32_e32 v34, 0x400, v0
	v_add_u32_e32 v34, 0x1000, v0
	v_add_u32_e32 v34, 0x1400, v0
	v_add_u32_e32 v34, 0x2000, v0
	v_add_u32_e32 v34, 0x2400, v0
	v_add_u32_e32 v34, 0x3000, v0
	v_add_u32_e32 v34, 0x3200, v0
	v_add_u32_e32 v34, 0x3400, v0
	v_add_u32_e32 v34, 0x3600, v0
	v_add_u32_e32 v34, 0x4000, v0
	v_add_u32_e32 v2, 0x4400, v0
	v_add_u32_e32 v2, 0x4800, v0
	v_add_u32_e32 v2, 0x5000, v0
	v_add_u32_e32 v2, 0x5400, v0
	v_add_u32_e32 v2, 0x5800, v0
	v_add_u32_e32 v2, 0x6000, v0
	v_add_u32_e32 v2, 0x6400, v0
	v_add_u32_e32 v2, 0x6800, v0
	v_add_u32_e32 v2, 0x7200, v0
	v_add_u32_e32 v2, 0x7400, v0
	v_add_u32_e32 v2, 0x7600, v0
	v_add_u32_e32 v0, 0x7800, v0
	v_mov_b32_e32 v8, v172
	s_waitcnt lgkmcnt(0)
	s_barrier
	s_cselect_b64 s[40:41], -1, 0
	v_ashrrev_i32_e32 v3, 1, v8
	v_lshl_add_u32 v0, v3, 2, v201
	s_cmp_lt_i32 s30, 24
	ds_read_b32 v2, v0
	s_cselect_b64 s[34:35], -1, 0
	s_cmp_gt_i32 s30, 40
	s_cselect_b64 s[56:57], -1, 0
	s_and_b64 s[36:37], s[36:37], s[56:57]
	s_or_b64 s[34:35], s[34:35], s[36:37]
	v_and_b32_e32 v13, 1, v8
	v_add_u32_e32 v4, s79, v3
	s_andn2_b64 vcc, exec, s[34:35]
	s_mov_b64 s[34:35], -1
	s_cbranch_vccnz .LBB1_390
	s_andn2_b64 vcc, exec, s[34:35]
	s_cbranch_vccnz .LBB1_383
	s_branch .LBB1_405
